# scan: next block's first operand reads issued right after the chunk barrier, ahead of the o-store code
# baseline (speedup 1.0000x reference)
; #define SCAN_BAR() asm volatile("s_barrier" ::: "memory")
; __device__ __forceinline__ void scan_unit(const Ctx& C0, const float* scn, int T, int quarter, const float* S0, float* Sout, unsigned char* obase, int mode) {
;     ...
;         float S0x = 0.f, S1x = 0.f, S2x = 0.f, S3x = 0.f;
;         if (S0) { const f32x4 t = *(const f32x4*)(S0 + irow * 64 + 4 * q); S0x = t.x; S1x = t.y; S2x = t.z; S3x = t.w; }
;         SCAN_BAR();
;         for (int k = 0; k < nch; ++k) {
;             const unsigned aq = (unsigned)(size_t)(C.lds + (k & 1) * SLOT_B) + 16u * (unsigned)q, av = (unsigned)(size_t)(C.lds + (k & 1) * SLOT_B) + (320u + (unsigned)irow) * 4u;
;             float osel0, osel1;
;             asm volatile(SCAN_CHUNK_ASM : "+v"(S0x), "+v"(S1x), "+v"(S2x), "+v"(S3x), "=&v"(osel0), "=&v"(osel1) : "v"(aq), "v"(av), "v"(q) : SCAN_CHUNK_CLOBBERS, "memory");
.LBB0_683:
	s_and_b64 vcc, exec, s[0:1]
	s_cbranch_vccz .LBB0_687
	v_lshrrev_b32_e32 v2, 4, v53
	s_lshl_b32 s1, s9, 2
	s_bfe_u32 s0, s72, 0x20003
	v_and_or_b32 v0, s1, 12, v2
	v_lshl_or_b32 v0, s0, 4, v0
	s_lshl_b32 s10, s2, 8
	s_lshl_b32 s0, s0, 6
	s_mul_i32 s9, s3, 0x5600000
	v_mov_b32_e32 v5, 0x500
	s_or_b32 s0, s10, s0
	s_mul_hi_i32 s1, s3, 0x5600000
	v_lshl_or_b32 v6, v0, 2, v5
	s_add_i32 s11, 0, 0xc000
	s_or_b32 s0, s9, s0
	s_waitcnt lgkmcnt(0)
	v_and_b32_e32 v3, 15, v52
	v_add_u32_e32 v9, 0, v6
	v_add_u32_e32 v11, s11, v6
	v_mov_b32_e32 v6, s0
	v_mov_b32_e32 v7, s1
	s_movk_i32 s0, 0x2b00
	v_mad_u64_u32 v[6:7], s[0:1], v3, s0, v[6:7]
	s_lshr_b32 s0, s8, 2
	s_and_b32 s0, s0, 48
	v_lshlrev_b32_e32 v2, 2, v2
	s_barrier
	v_or3_b32 v6, s0, v2, v6
	v_readlane_b32 s0, v253, 4
	v_lshlrev_b32_e32 v4, 4, v3
	v_readlane_b32 s1, v253, 5
	v_add_u32_e32 v5, 0, v4
	v_add_u32_e32 v10, s11, v4
	v_lshl_add_u64 v[6:7], s[0:1], 0, v[6:7]
	v_mov_b32_e32 v8, 0
	s_mov_b64 s[0:1], 0
	v_mov_b32_e32 v12, 0
	v_mov_b32_e32 v13, 0
	v_mov_b32_e32 v2, 0
	v_mov_b32_e32 v138, v2
	v_mov_b32_e32 v139, v13
	v_mov_b32_e32 v140, v12
	v_mov_b32_e32 v141, v8
	ds_read_b128 v[164:167], v5 offset:0
	ds_read_b128 v[168:171], v5 offset:256
	ds_read_b128 v[172:175], v5 offset:512
	ds_read_b128 v[176:179], v5 offset:768
	ds_read_b128 v[180:183], v5 offset:1024
	ds_read_b32 v184, v9 offset:0
	ds_read_b128 v[186:189], v5 offset:1536
	ds_read_b128 v[190:193], v5 offset:1792
	ds_read_b128 v[194:197], v5 offset:2048
	ds_read_b128 v[198:201], v5 offset:2304
	ds_read_b128 v[202:205], v5 offset:2560
	ds_read_b32 v206, v9 offset:1536
.LBB0_685:
	s_waitcnt lgkmcnt(6)
	v_pk_mul_f32 v[144:145], v[138:139], v[164:165]
	v_pk_fma_f32 v[144:145], v[140:141], v[166:167], v[144:145]
	v_add_f32 v146, v144, v145
	ds_read_b128 v[208:211], v5 offset:3072
	ds_read_b128 v[212:215], v5 offset:3328
	ds_read_b128 v[216:219], v5 offset:3584
	ds_read_b128 v[220:223], v5 offset:3840
	ds_read_b128 v[224:227], v5 offset:4096
	ds_read_b32 v228, v9 offset:3072
	v_add_f32_dpp v146, v146, v146 quad_perm:[1,0,3,2] row_mask:0xf bank_mask:0xf bound_ctrl:1
	s_nop 0
	s_nop 0
	v_add_f32_dpp v146, v146, v146 quad_perm:[2,3,0,1] row_mask:0xf bank_mask:0xf bound_ctrl:1
	s_nop 0
	v_pk_mul_f32 v[176:177], v[176:177], v[184:185] op_sel_hi:[1,0]
	v_add_f32_dpp v146, v146, v146 row_half_mirror row_mask:0xf bank_mask:0xf bound_ctrl:1
	v_pk_mul_f32 v[178:179], v[178:179], v[184:185] op_sel_hi:[1,0]
	s_waitcnt lgkmcnt(6)
	v_add_f32_dpp v146, v146, v146 row_mirror row_mask:0xf bank_mask:0xf bound_ctrl:1
	v_pk_fma_f32 v[176:177], v[146:147], v[168:169], v[176:177] op_sel_hi:[0,1,1] neg_lo:[1,0,0] neg_hi:[1,0,0]
	v_pk_fma_f32 v[178:179], v[146:147], v[170:171], v[178:179] op_sel_hi:[0,1,1] neg_lo:[1,0,0] neg_hi:[1,0,0]
	v_pk_fma_f32 v[138:139], v[138:139], v[172:173], v[176:177]
	v_pk_fma_f32 v[140:141], v[140:141], v[174:175], v[178:179]
	v_pk_mul_f32 v[144:145], v[138:139], v[186:187]
	v_pk_fma_f32 v[144:145], v[140:141], v[188:189], v[144:145]
	v_add_f32 v146, v144, v145
	ds_read_b128 v[230:233], v5 offset:4608
	ds_read_b128 v[234:237], v5 offset:4864
	ds_read_b128 v[238:241], v5 offset:5120
	ds_read_b128 v[242:245], v5 offset:5376
	ds_read_b128 v[246:249], v5 offset:5632
	ds_read_b32 v250, v9 offset:4608
	v_add_f32_dpp v146, v146, v146 quad_perm:[1,0,3,2] row_mask:0xf bank_mask:0xf bound_ctrl:1
	v_pk_mul_f32 v[180:181], v[138:139], v[180:181]
	v_pk_fma_f32 v[180:181], v[140:141], v[182:183], v[180:181]
	v_add_f32_dpp v146, v146, v146 quad_perm:[2,3,0,1] row_mask:0xf bank_mask:0xf bound_ctrl:1
	v_add_f32 v148, v180, v181
	v_pk_mul_f32 v[198:199], v[198:199], v[206:207] op_sel_hi:[1,0]
	v_add_f32_dpp v146, v146, v146 row_half_mirror row_mask:0xf bank_mask:0xf bound_ctrl:1
	v_pk_mul_f32 v[200:201], v[200:201], v[206:207] op_sel_hi:[1,0]
	s_waitcnt lgkmcnt(6)
	v_add_f32_dpp v146, v146, v146 row_mirror row_mask:0xf bank_mask:0xf bound_ctrl:1
	v_pk_fma_f32 v[198:199], v[146:147], v[190:191], v[198:199] op_sel_hi:[0,1,1] neg_lo:[1,0,0] neg_hi:[1,0,0]
	v_pk_fma_f32 v[200:201], v[146:147], v[192:193], v[200:201] op_sel_hi:[0,1,1] neg_lo:[1,0,0] neg_hi:[1,0,0]
	v_pk_fma_f32 v[138:139], v[138:139], v[194:195], v[198:199]
	v_pk_fma_f32 v[140:141], v[140:141], v[196:197], v[200:201]
	v_pk_mul_f32 v[144:145], v[138:139], v[208:209]
	v_pk_fma_f32 v[144:145], v[140:141], v[210:211], v[144:145]
	v_add_f32 v146, v144, v145
	ds_read_b128 v[164:167], v5 offset:6144
	ds_read_b128 v[168:171], v5 offset:6400
	ds_read_b128 v[172:175], v5 offset:6656
	ds_read_b128 v[176:179], v5 offset:6912
	ds_read_b128 v[180:183], v5 offset:7168
	ds_read_b32 v184, v9 offset:6144
	v_add_f32_dpp v146, v146, v146 quad_perm:[1,0,3,2] row_mask:0xf bank_mask:0xf bound_ctrl:1
	v_pk_mul_f32 v[202:203], v[138:139], v[202:203]
	v_pk_fma_f32 v[202:203], v[140:141], v[204:205], v[202:203]
	v_add_f32_dpp v146, v146, v146 quad_perm:[2,3,0,1] row_mask:0xf bank_mask:0xf bound_ctrl:1
	v_add_f32 v149, v202, v203
	v_pk_mul_f32 v[220:221], v[220:221], v[228:229] op_sel_hi:[1,0]
	v_add_f32_dpp v146, v146, v146 row_half_mirror row_mask:0xf bank_mask:0xf bound_ctrl:1
	v_pk_mul_f32 v[222:223], v[222:223], v[228:229] op_sel_hi:[1,0]
	s_waitcnt lgkmcnt(6)
	v_add_f32_dpp v146, v146, v146 row_mirror row_mask:0xf bank_mask:0xf bound_ctrl:1
	v_pk_fma_f32 v[220:221], v[146:147], v[212:213], v[220:221] op_sel_hi:[0,1,1] neg_lo:[1,0,0] neg_hi:[1,0,0]
	v_pk_fma_f32 v[222:223], v[146:147], v[214:215], v[222:223] op_sel_hi:[0,1,1] neg_lo:[1,0,0] neg_hi:[1,0,0]
	v_pk_fma_f32 v[138:139], v[138:139], v[216:217], v[220:221]
	v_pk_fma_f32 v[140:141], v[140:141], v[218:219], v[222:223]
	v_pk_mul_f32 v[144:145], v[138:139], v[230:231]
	v_pk_fma_f32 v[144:145], v[140:141], v[232:233], v[144:145]
	v_add_f32 v146, v144, v145
	ds_read_b128 v[186:189], v5 offset:7680
	ds_read_b128 v[190:193], v5 offset:7936
	ds_read_b128 v[194:197], v5 offset:8192
	ds_read_b128 v[198:201], v5 offset:8448
	ds_read_b128 v[202:205], v5 offset:8704
	ds_read_b32 v206, v9 offset:7680
	v_add_f32_dpp v146, v146, v146 quad_perm:[1,0,3,2] row_mask:0xf bank_mask:0xf bound_ctrl:1
	v_pk_mul_f32 v[224:225], v[138:139], v[224:225]
	v_pk_fma_f32 v[224:225], v[140:141], v[226:227], v[224:225]
	v_add_f32_dpp v146, v146, v146 quad_perm:[2,3,0,1] row_mask:0xf bank_mask:0xf bound_ctrl:1
	v_add_f32 v150, v224, v225
	v_pk_mul_f32 v[242:243], v[242:243], v[250:251] op_sel_hi:[1,0]
	v_add_f32_dpp v146, v146, v146 row_half_mirror row_mask:0xf bank_mask:0xf bound_ctrl:1
	v_pk_mul_f32 v[244:245], v[244:245], v[250:251] op_sel_hi:[1,0]
	s_waitcnt lgkmcnt(6)
	v_add_f32_dpp v146, v146, v146 row_mirror row_mask:0xf bank_mask:0xf bound_ctrl:1
	v_pk_fma_f32 v[242:243], v[146:147], v[234:235], v[242:243] op_sel_hi:[0,1,1] neg_lo:[1,0,0] neg_hi:[1,0,0]
	v_pk_fma_f32 v[244:245], v[146:147], v[236:237], v[244:245] op_sel_hi:[0,1,1] neg_lo:[1,0,0] neg_hi:[1,0,0]
	v_pk_fma_f32 v[138:139], v[138:139], v[238:239], v[242:243]
	v_pk_fma_f32 v[140:141], v[140:141], v[240:241], v[244:245]
	v_pk_mul_f32 v[144:145], v[138:139], v[164:165]
	v_pk_fma_f32 v[144:145], v[140:141], v[166:167], v[144:145]
	v_add_f32 v146, v144, v145
	ds_read_b128 v[208:211], v5 offset:9216
	ds_read_b128 v[212:215], v5 offset:9472
	ds_read_b128 v[216:219], v5 offset:9728
	ds_read_b128 v[220:223], v5 offset:9984
	ds_read_b128 v[224:227], v5 offset:10240
	ds_read_b32 v228, v9 offset:9216
	v_add_f32_dpp v146, v146, v146 quad_perm:[1,0,3,2] row_mask:0xf bank_mask:0xf bound_ctrl:1
	v_pk_mul_f32 v[246:247], v[138:139], v[246:247]
	v_pk_fma_f32 v[246:247], v[140:141], v[248:249], v[246:247]
	v_add_f32_dpp v146, v146, v146 quad_perm:[2,3,0,1] row_mask:0xf bank_mask:0xf bound_ctrl:1
	v_add_f32 v151, v246, v247
	v_pk_mul_f32 v[176:177], v[176:177], v[184:185] op_sel_hi:[1,0]
	v_add_f32_dpp v146, v146, v146 row_half_mirror row_mask:0xf bank_mask:0xf bound_ctrl:1
	v_pk_mul_f32 v[178:179], v[178:179], v[184:185] op_sel_hi:[1,0]
	s_waitcnt lgkmcnt(6)
	v_add_f32_dpp v146, v146, v146 row_mirror row_mask:0xf bank_mask:0xf bound_ctrl:1
	v_pk_fma_f32 v[176:177], v[146:147], v[168:169], v[176:177] op_sel_hi:[0,1,1] neg_lo:[1,0,0] neg_hi:[1,0,0]
	v_pk_fma_f32 v[178:179], v[146:147], v[170:171], v[178:179] op_sel_hi:[0,1,1] neg_lo:[1,0,0] neg_hi:[1,0,0]
	v_pk_fma_f32 v[138:139], v[138:139], v[172:173], v[176:177]
	v_pk_fma_f32 v[140:141], v[140:141], v[174:175], v[178:179]
	v_pk_mul_f32 v[144:145], v[138:139], v[186:187]
	v_pk_fma_f32 v[144:145], v[140:141], v[188:189], v[144:145]
	v_add_f32 v146, v144, v145
	ds_read_b128 v[230:233], v5 offset:10752
	ds_read_b128 v[234:237], v5 offset:11008
	ds_read_b128 v[238:241], v5 offset:11264
	ds_read_b128 v[242:245], v5 offset:11520
	ds_read_b128 v[246:249], v5 offset:11776
	ds_read_b32 v250, v9 offset:10752
	v_add_f32_dpp v146, v146, v146 quad_perm:[1,0,3,2] row_mask:0xf bank_mask:0xf bound_ctrl:1
	v_pk_mul_f32 v[180:181], v[138:139], v[180:181]
	v_pk_fma_f32 v[180:181], v[140:141], v[182:183], v[180:181]
	v_add_f32_dpp v146, v146, v146 quad_perm:[2,3,0,1] row_mask:0xf bank_mask:0xf bound_ctrl:1
	v_add_f32 v152, v180, v181
	v_pk_mul_f32 v[198:199], v[198:199], v[206:207] op_sel_hi:[1,0]
	v_add_f32_dpp v146, v146, v146 row_half_mirror row_mask:0xf bank_mask:0xf bound_ctrl:1
	v_pk_mul_f32 v[200:201], v[200:201], v[206:207] op_sel_hi:[1,0]
	s_waitcnt lgkmcnt(6)
	v_add_f32_dpp v146, v146, v146 row_mirror row_mask:0xf bank_mask:0xf bound_ctrl:1
	v_pk_fma_f32 v[198:199], v[146:147], v[190:191], v[198:199] op_sel_hi:[0,1,1] neg_lo:[1,0,0] neg_hi:[1,0,0]
	v_pk_fma_f32 v[200:201], v[146:147], v[192:193], v[200:201] op_sel_hi:[0,1,1] neg_lo:[1,0,0] neg_hi:[1,0,0]
	v_pk_fma_f32 v[138:139], v[138:139], v[194:195], v[198:199]
	v_pk_fma_f32 v[140:141], v[140:141], v[196:197], v[200:201]
	v_pk_mul_f32 v[144:145], v[138:139], v[208:209]
	v_pk_fma_f32 v[144:145], v[140:141], v[210:211], v[144:145]
	v_add_f32 v146, v144, v145
	ds_read_b128 v[164:167], v5 offset:12288
	ds_read_b128 v[168:171], v5 offset:12544
	ds_read_b128 v[172:175], v5 offset:12800
	ds_read_b128 v[176:179], v5 offset:13056
	ds_read_b128 v[180:183], v5 offset:13312
	ds_read_b32 v184, v9 offset:12288
	v_add_f32_dpp v146, v146, v146 quad_perm:[1,0,3,2] row_mask:0xf bank_mask:0xf bound_ctrl:1
	v_pk_mul_f32 v[202:203], v[138:139], v[202:203]
	v_pk_fma_f32 v[202:203], v[140:141], v[204:205], v[202:203]
	v_add_f32_dpp v146, v146, v146 quad_perm:[2,3,0,1] row_mask:0xf bank_mask:0xf bound_ctrl:1
	v_add_f32 v153, v202, v203
	v_pk_mul_f32 v[220:221], v[220:221], v[228:229] op_sel_hi:[1,0]
	v_add_f32_dpp v146, v146, v146 row_half_mirror row_mask:0xf bank_mask:0xf bound_ctrl:1
	v_pk_mul_f32 v[222:223], v[222:223], v[228:229] op_sel_hi:[1,0]
	s_waitcnt lgkmcnt(6)
	v_add_f32_dpp v146, v146, v146 row_mirror row_mask:0xf bank_mask:0xf bound_ctrl:1
	v_pk_fma_f32 v[220:221], v[146:147], v[212:213], v[220:221] op_sel_hi:[0,1,1] neg_lo:[1,0,0] neg_hi:[1,0,0]
	v_pk_fma_f32 v[222:223], v[146:147], v[214:215], v[222:223] op_sel_hi:[0,1,1] neg_lo:[1,0,0] neg_hi:[1,0,0]
	v_pk_fma_f32 v[138:139], v[138:139], v[216:217], v[220:221]
	v_pk_fma_f32 v[140:141], v[140:141], v[218:219], v[222:223]
	v_pk_mul_f32 v[144:145], v[138:139], v[230:231]
	v_pk_fma_f32 v[144:145], v[140:141], v[232:233], v[144:145]
	v_add_f32 v146, v144, v145
	ds_read_b128 v[186:189], v5 offset:13824
	ds_read_b128 v[190:193], v5 offset:14080
	ds_read_b128 v[194:197], v5 offset:14336
	ds_read_b128 v[198:201], v5 offset:14592
	ds_read_b128 v[202:205], v5 offset:14848
	ds_read_b32 v206, v9 offset:13824
	v_add_f32_dpp v146, v146, v146 quad_perm:[1,0,3,2] row_mask:0xf bank_mask:0xf bound_ctrl:1
	v_pk_mul_f32 v[224:225], v[138:139], v[224:225]
	v_pk_fma_f32 v[224:225], v[140:141], v[226:227], v[224:225]
	v_add_f32_dpp v146, v146, v146 quad_perm:[2,3,0,1] row_mask:0xf bank_mask:0xf bound_ctrl:1
	v_add_f32 v154, v224, v225
	v_pk_mul_f32 v[242:243], v[242:243], v[250:251] op_sel_hi:[1,0]
	v_add_f32_dpp v146, v146, v146 row_half_mirror row_mask:0xf bank_mask:0xf bound_ctrl:1
	v_pk_mul_f32 v[244:245], v[244:245], v[250:251] op_sel_hi:[1,0]
	s_waitcnt lgkmcnt(6)
	v_add_f32_dpp v146, v146, v146 row_mirror row_mask:0xf bank_mask:0xf bound_ctrl:1
	v_pk_fma_f32 v[242:243], v[146:147], v[234:235], v[242:243] op_sel_hi:[0,1,1] neg_lo:[1,0,0] neg_hi:[1,0,0]
	v_pk_fma_f32 v[244:245], v[146:147], v[236:237], v[244:245] op_sel_hi:[0,1,1] neg_lo:[1,0,0] neg_hi:[1,0,0]
	v_pk_fma_f32 v[138:139], v[138:139], v[238:239], v[242:243]
	v_pk_fma_f32 v[140:141], v[140:141], v[240:241], v[244:245]
	v_pk_mul_f32 v[144:145], v[138:139], v[164:165]
	v_pk_fma_f32 v[144:145], v[140:141], v[166:167], v[144:145]
	v_add_f32 v146, v144, v145
	ds_read_b128 v[208:211], v5 offset:15360
	ds_read_b128 v[212:215], v5 offset:15616
	ds_read_b128 v[216:219], v5 offset:15872
	ds_read_b128 v[220:223], v5 offset:16128
	ds_read_b128 v[224:227], v5 offset:16384
	ds_read_b32 v228, v9 offset:15360
	v_add_f32_dpp v146, v146, v146 quad_perm:[1,0,3,2] row_mask:0xf bank_mask:0xf bound_ctrl:1
	v_pk_mul_f32 v[246:247], v[138:139], v[246:247]
	v_pk_fma_f32 v[246:247], v[140:141], v[248:249], v[246:247]
	v_add_f32_dpp v146, v146, v146 quad_perm:[2,3,0,1] row_mask:0xf bank_mask:0xf bound_ctrl:1
	v_add_f32 v155, v246, v247
	v_pk_mul_f32 v[176:177], v[176:177], v[184:185] op_sel_hi:[1,0]
	v_add_f32_dpp v146, v146, v146 row_half_mirror row_mask:0xf bank_mask:0xf bound_ctrl:1
	v_pk_mul_f32 v[178:179], v[178:179], v[184:185] op_sel_hi:[1,0]
	s_waitcnt lgkmcnt(6)
	v_add_f32_dpp v146, v146, v146 row_mirror row_mask:0xf bank_mask:0xf bound_ctrl:1
	v_pk_fma_f32 v[176:177], v[146:147], v[168:169], v[176:177] op_sel_hi:[0,1,1] neg_lo:[1,0,0] neg_hi:[1,0,0]
	v_pk_fma_f32 v[178:179], v[146:147], v[170:171], v[178:179] op_sel_hi:[0,1,1] neg_lo:[1,0,0] neg_hi:[1,0,0]
	v_pk_fma_f32 v[138:139], v[138:139], v[172:173], v[176:177]
	v_pk_fma_f32 v[140:141], v[140:141], v[174:175], v[178:179]
	v_pk_mul_f32 v[144:145], v[138:139], v[186:187]
	v_pk_fma_f32 v[144:145], v[140:141], v[188:189], v[144:145]
	v_add_f32 v146, v144, v145
	ds_read_b128 v[230:233], v5 offset:16896
	ds_read_b128 v[234:237], v5 offset:17152
	ds_read_b128 v[238:241], v5 offset:17408
	ds_read_b128 v[242:245], v5 offset:17664
	ds_read_b128 v[246:249], v5 offset:17920
	ds_read_b32 v250, v9 offset:16896
	v_add_f32_dpp v146, v146, v146 quad_perm:[1,0,3,2] row_mask:0xf bank_mask:0xf bound_ctrl:1
	v_pk_mul_f32 v[180:181], v[138:139], v[180:181]
	v_pk_fma_f32 v[180:181], v[140:141], v[182:183], v[180:181]
	v_add_f32_dpp v146, v146, v146 quad_perm:[2,3,0,1] row_mask:0xf bank_mask:0xf bound_ctrl:1
	v_add_f32 v156, v180, v181
	v_pk_mul_f32 v[198:199], v[198:199], v[206:207] op_sel_hi:[1,0]
	v_add_f32_dpp v146, v146, v146 row_half_mirror row_mask:0xf bank_mask:0xf bound_ctrl:1
	v_pk_mul_f32 v[200:201], v[200:201], v[206:207] op_sel_hi:[1,0]
	s_waitcnt lgkmcnt(6)
	v_add_f32_dpp v146, v146, v146 row_mirror row_mask:0xf bank_mask:0xf bound_ctrl:1
	v_pk_fma_f32 v[198:199], v[146:147], v[190:191], v[198:199] op_sel_hi:[0,1,1] neg_lo:[1,0,0] neg_hi:[1,0,0]
	v_pk_fma_f32 v[200:201], v[146:147], v[192:193], v[200:201] op_sel_hi:[0,1,1] neg_lo:[1,0,0] neg_hi:[1,0,0]
	v_pk_fma_f32 v[138:139], v[138:139], v[194:195], v[198:199]
	v_pk_fma_f32 v[140:141], v[140:141], v[196:197], v[200:201]
	v_pk_mul_f32 v[144:145], v[138:139], v[208:209]
	v_pk_fma_f32 v[144:145], v[140:141], v[210:211], v[144:145]
	v_add_f32 v146, v144, v145
	ds_read_b128 v[164:167], v5 offset:18432
	ds_read_b128 v[168:171], v5 offset:18688
	ds_read_b128 v[172:175], v5 offset:18944
	ds_read_b128 v[176:179], v5 offset:19200
	ds_read_b128 v[180:183], v5 offset:19456
	ds_read_b32 v184, v9 offset:18432
	v_add_f32_dpp v146, v146, v146 quad_perm:[1,0,3,2] row_mask:0xf bank_mask:0xf bound_ctrl:1
	v_pk_mul_f32 v[202:203], v[138:139], v[202:203]
	v_pk_fma_f32 v[202:203], v[140:141], v[204:205], v[202:203]
	v_add_f32_dpp v146, v146, v146 quad_perm:[2,3,0,1] row_mask:0xf bank_mask:0xf bound_ctrl:1
	v_add_f32 v157, v202, v203
	v_pk_mul_f32 v[220:221], v[220:221], v[228:229] op_sel_hi:[1,0]
	v_add_f32_dpp v146, v146, v146 row_half_mirror row_mask:0xf bank_mask:0xf bound_ctrl:1
	v_pk_mul_f32 v[222:223], v[222:223], v[228:229] op_sel_hi:[1,0]
	s_waitcnt lgkmcnt(6)
	v_add_f32_dpp v146, v146, v146 row_mirror row_mask:0xf bank_mask:0xf bound_ctrl:1
	v_pk_fma_f32 v[220:221], v[146:147], v[212:213], v[220:221] op_sel_hi:[0,1,1] neg_lo:[1,0,0] neg_hi:[1,0,0]
	v_pk_fma_f32 v[222:223], v[146:147], v[214:215], v[222:223] op_sel_hi:[0,1,1] neg_lo:[1,0,0] neg_hi:[1,0,0]
	v_pk_fma_f32 v[138:139], v[138:139], v[216:217], v[220:221]
	v_pk_fma_f32 v[140:141], v[140:141], v[218:219], v[222:223]
	v_pk_mul_f32 v[144:145], v[138:139], v[230:231]
	v_pk_fma_f32 v[144:145], v[140:141], v[232:233], v[144:145]
	v_add_f32 v146, v144, v145
	ds_read_b128 v[186:189], v5 offset:19968
	ds_read_b128 v[190:193], v5 offset:20224
	ds_read_b128 v[194:197], v5 offset:20480
	ds_read_b128 v[198:201], v5 offset:20736
	ds_read_b128 v[202:205], v5 offset:20992
	ds_read_b32 v206, v9 offset:19968
	v_add_f32_dpp v146, v146, v146 quad_perm:[1,0,3,2] row_mask:0xf bank_mask:0xf bound_ctrl:1
	v_pk_mul_f32 v[224:225], v[138:139], v[224:225]
	v_pk_fma_f32 v[224:225], v[140:141], v[226:227], v[224:225]
	v_add_f32_dpp v146, v146, v146 quad_perm:[2,3,0,1] row_mask:0xf bank_mask:0xf bound_ctrl:1
	v_add_f32 v158, v224, v225
	v_pk_mul_f32 v[242:243], v[242:243], v[250:251] op_sel_hi:[1,0]
	v_add_f32_dpp v146, v146, v146 row_half_mirror row_mask:0xf bank_mask:0xf bound_ctrl:1
	v_pk_mul_f32 v[244:245], v[244:245], v[250:251] op_sel_hi:[1,0]
	s_waitcnt lgkmcnt(6)
	v_add_f32_dpp v146, v146, v146 row_mirror row_mask:0xf bank_mask:0xf bound_ctrl:1
	v_pk_fma_f32 v[242:243], v[146:147], v[234:235], v[242:243] op_sel_hi:[0,1,1] neg_lo:[1,0,0] neg_hi:[1,0,0]
	v_pk_fma_f32 v[244:245], v[146:147], v[236:237], v[244:245] op_sel_hi:[0,1,1] neg_lo:[1,0,0] neg_hi:[1,0,0]
	v_pk_fma_f32 v[138:139], v[138:139], v[238:239], v[242:243]
	v_pk_fma_f32 v[140:141], v[140:141], v[240:241], v[244:245]
	v_pk_mul_f32 v[144:145], v[138:139], v[164:165]
	v_pk_fma_f32 v[144:145], v[140:141], v[166:167], v[144:145]
	v_add_f32 v146, v144, v145
	ds_read_b128 v[208:211], v5 offset:21504
	ds_read_b128 v[212:215], v5 offset:21760
	ds_read_b128 v[216:219], v5 offset:22016
	ds_read_b128 v[220:223], v5 offset:22272
	ds_read_b128 v[224:227], v5 offset:22528
	ds_read_b32 v228, v9 offset:21504
	v_add_f32_dpp v146, v146, v146 quad_perm:[1,0,3,2] row_mask:0xf bank_mask:0xf bound_ctrl:1
	v_pk_mul_f32 v[246:247], v[138:139], v[246:247]
	v_pk_fma_f32 v[246:247], v[140:141], v[248:249], v[246:247]
	v_add_f32_dpp v146, v146, v146 quad_perm:[2,3,0,1] row_mask:0xf bank_mask:0xf bound_ctrl:1
	v_add_f32 v159, v246, v247
	v_pk_mul_f32 v[176:177], v[176:177], v[184:185] op_sel_hi:[1,0]
	v_add_f32_dpp v146, v146, v146 row_half_mirror row_mask:0xf bank_mask:0xf bound_ctrl:1
	v_pk_mul_f32 v[178:179], v[178:179], v[184:185] op_sel_hi:[1,0]
	s_waitcnt lgkmcnt(6)
	v_add_f32_dpp v146, v146, v146 row_mirror row_mask:0xf bank_mask:0xf bound_ctrl:1
	v_pk_fma_f32 v[176:177], v[146:147], v[168:169], v[176:177] op_sel_hi:[0,1,1] neg_lo:[1,0,0] neg_hi:[1,0,0]
	v_pk_fma_f32 v[178:179], v[146:147], v[170:171], v[178:179] op_sel_hi:[0,1,1] neg_lo:[1,0,0] neg_hi:[1,0,0]
	v_pk_fma_f32 v[138:139], v[138:139], v[172:173], v[176:177]
	v_pk_fma_f32 v[140:141], v[140:141], v[174:175], v[178:179]
	v_pk_mul_f32 v[144:145], v[138:139], v[186:187]
	v_pk_fma_f32 v[144:145], v[140:141], v[188:189], v[144:145]
	v_add_f32 v146, v144, v145
	ds_read_b128 v[230:233], v5 offset:23040
	ds_read_b128 v[234:237], v5 offset:23296
	ds_read_b128 v[238:241], v5 offset:23552
	ds_read_b128 v[242:245], v5 offset:23808
	ds_read_b128 v[246:249], v5 offset:24064
	ds_read_b32 v250, v9 offset:23040
	v_add_f32_dpp v146, v146, v146 quad_perm:[1,0,3,2] row_mask:0xf bank_mask:0xf bound_ctrl:1
	v_pk_mul_f32 v[180:181], v[138:139], v[180:181]
	v_pk_fma_f32 v[180:181], v[140:141], v[182:183], v[180:181]
	v_add_f32_dpp v146, v146, v146 quad_perm:[2,3,0,1] row_mask:0xf bank_mask:0xf bound_ctrl:1
	v_add_f32 v160, v180, v181
	v_pk_mul_f32 v[198:199], v[198:199], v[206:207] op_sel_hi:[1,0]
	v_add_f32_dpp v146, v146, v146 row_half_mirror row_mask:0xf bank_mask:0xf bound_ctrl:1
	v_pk_mul_f32 v[200:201], v[200:201], v[206:207] op_sel_hi:[1,0]
	s_waitcnt lgkmcnt(6)
	v_add_f32_dpp v146, v146, v146 row_mirror row_mask:0xf bank_mask:0xf bound_ctrl:1
	v_pk_fma_f32 v[198:199], v[146:147], v[190:191], v[198:199] op_sel_hi:[0,1,1] neg_lo:[1,0,0] neg_hi:[1,0,0]
	v_pk_fma_f32 v[200:201], v[146:147], v[192:193], v[200:201] op_sel_hi:[0,1,1] neg_lo:[1,0,0] neg_hi:[1,0,0]
	v_pk_fma_f32 v[138:139], v[138:139], v[194:195], v[198:199]
	v_pk_fma_f32 v[140:141], v[140:141], v[196:197], v[200:201]
	v_pk_mul_f32 v[144:145], v[138:139], v[208:209]
	v_pk_fma_f32 v[144:145], v[140:141], v[210:211], v[144:145]
	v_add_f32 v146, v144, v145
	ds_read_b128 v[164:167], v5 offset:24576
	ds_read_b128 v[168:171], v5 offset:24832
	ds_read_b128 v[172:175], v5 offset:25088
	ds_read_b128 v[176:179], v5 offset:25344
	ds_read_b128 v[180:183], v5 offset:25600
	ds_read_b32 v184, v9 offset:24576
	v_add_f32_dpp v146, v146, v146 quad_perm:[1,0,3,2] row_mask:0xf bank_mask:0xf bound_ctrl:1
	v_pk_mul_f32 v[202:203], v[138:139], v[202:203]
	v_pk_fma_f32 v[202:203], v[140:141], v[204:205], v[202:203]
	v_add_f32_dpp v146, v146, v146 quad_perm:[2,3,0,1] row_mask:0xf bank_mask:0xf bound_ctrl:1
	v_add_f32 v161, v202, v203
	v_pk_mul_f32 v[220:221], v[220:221], v[228:229] op_sel_hi:[1,0]
	v_add_f32_dpp v146, v146, v146 row_half_mirror row_mask:0xf bank_mask:0xf bound_ctrl:1
	v_pk_mul_f32 v[222:223], v[222:223], v[228:229] op_sel_hi:[1,0]
	s_waitcnt lgkmcnt(6)
	v_add_f32_dpp v146, v146, v146 row_mirror row_mask:0xf bank_mask:0xf bound_ctrl:1
	v_pk_fma_f32 v[220:221], v[146:147], v[212:213], v[220:221] op_sel_hi:[0,1,1] neg_lo:[1,0,0] neg_hi:[1,0,0]
	v_pk_fma_f32 v[222:223], v[146:147], v[214:215], v[222:223] op_sel_hi:[0,1,1] neg_lo:[1,0,0] neg_hi:[1,0,0]
	v_pk_fma_f32 v[138:139], v[138:139], v[216:217], v[220:221]
	v_pk_fma_f32 v[140:141], v[140:141], v[218:219], v[222:223]
	v_pk_mul_f32 v[144:145], v[138:139], v[230:231]
	v_pk_fma_f32 v[144:145], v[140:141], v[232:233], v[144:145]
	v_add_f32 v146, v144, v145
	ds_read_b128 v[186:189], v5 offset:26112
	ds_read_b128 v[190:193], v5 offset:26368
	ds_read_b128 v[194:197], v5 offset:26624
	ds_read_b128 v[198:201], v5 offset:26880
	ds_read_b128 v[202:205], v5 offset:27136
	ds_read_b32 v206, v9 offset:26112
	v_add_f32_dpp v146, v146, v146 quad_perm:[1,0,3,2] row_mask:0xf bank_mask:0xf bound_ctrl:1
	v_pk_mul_f32 v[224:225], v[138:139], v[224:225]
	v_pk_fma_f32 v[224:225], v[140:141], v[226:227], v[224:225]
	v_add_f32_dpp v146, v146, v146 quad_perm:[2,3,0,1] row_mask:0xf bank_mask:0xf bound_ctrl:1
	v_add_f32 v162, v224, v225
	v_pk_mul_f32 v[242:243], v[242:243], v[250:251] op_sel_hi:[1,0]
	v_add_f32_dpp v146, v146, v146 row_half_mirror row_mask:0xf bank_mask:0xf bound_ctrl:1
	v_pk_mul_f32 v[244:245], v[244:245], v[250:251] op_sel_hi:[1,0]
	s_waitcnt lgkmcnt(6)
	v_add_f32_dpp v146, v146, v146 row_mirror row_mask:0xf bank_mask:0xf bound_ctrl:1
	v_pk_fma_f32 v[242:243], v[146:147], v[234:235], v[242:243] op_sel_hi:[0,1,1] neg_lo:[1,0,0] neg_hi:[1,0,0]
	v_pk_fma_f32 v[244:245], v[146:147], v[236:237], v[244:245] op_sel_hi:[0,1,1] neg_lo:[1,0,0] neg_hi:[1,0,0]
	v_pk_fma_f32 v[138:139], v[138:139], v[238:239], v[242:243]
	v_pk_fma_f32 v[140:141], v[140:141], v[240:241], v[244:245]
	v_pk_mul_f32 v[144:145], v[138:139], v[164:165]
	v_pk_fma_f32 v[144:145], v[140:141], v[166:167], v[144:145]
	v_add_f32 v146, v144, v145
	ds_read_b128 v[208:211], v5 offset:27648
	ds_read_b128 v[212:215], v5 offset:27904
	ds_read_b128 v[216:219], v5 offset:28160
	ds_read_b128 v[220:223], v5 offset:28416
	ds_read_b128 v[224:227], v5 offset:28672
	ds_read_b32 v228, v9 offset:27648
	v_add_f32_dpp v146, v146, v146 quad_perm:[1,0,3,2] row_mask:0xf bank_mask:0xf bound_ctrl:1
	v_pk_mul_f32 v[246:247], v[138:139], v[246:247]
	v_pk_fma_f32 v[246:247], v[140:141], v[248:249], v[246:247]
	v_add_f32_dpp v146, v146, v146 quad_perm:[2,3,0,1] row_mask:0xf bank_mask:0xf bound_ctrl:1
	v_add_f32 v163, v246, v247
	v_pk_mul_f32 v[176:177], v[176:177], v[184:185] op_sel_hi:[1,0]
	v_add_f32_dpp v146, v146, v146 row_half_mirror row_mask:0xf bank_mask:0xf bound_ctrl:1
	v_pk_mul_f32 v[178:179], v[178:179], v[184:185] op_sel_hi:[1,0]
	s_waitcnt lgkmcnt(6)
	v_add_f32_dpp v146, v146, v146 row_mirror row_mask:0xf bank_mask:0xf bound_ctrl:1
	v_pk_fma_f32 v[176:177], v[146:147], v[168:169], v[176:177] op_sel_hi:[0,1,1] neg_lo:[1,0,0] neg_hi:[1,0,0]
	v_pk_fma_f32 v[178:179], v[146:147], v[170:171], v[178:179] op_sel_hi:[0,1,1] neg_lo:[1,0,0] neg_hi:[1,0,0]
	v_pk_fma_f32 v[138:139], v[138:139], v[172:173], v[176:177]
	v_pk_fma_f32 v[140:141], v[140:141], v[174:175], v[178:179]
	v_pk_mul_f32 v[144:145], v[138:139], v[186:187]
	v_pk_fma_f32 v[144:145], v[140:141], v[188:189], v[144:145]
	v_add_f32 v146, v144, v145
	v_add_f32_dpp v230, v148, v148 row_mirror row_mask:0xf bank_mask:0x3 bound_ctrl:1
	v_add_f32_dpp v230, v156, v156 row_mirror row_mask:0xf bank_mask:0xc bound_ctrl:1
	v_add_f32_dpp v231, v149, v149 row_mirror row_mask:0xf bank_mask:0x3 bound_ctrl:1
	v_add_f32_dpp v231, v157, v157 row_mirror row_mask:0xf bank_mask:0xc bound_ctrl:1
	v_add_f32_dpp v232, v150, v150 row_mirror row_mask:0xf bank_mask:0x3 bound_ctrl:1
	v_add_f32_dpp v232, v158, v158 row_mirror row_mask:0xf bank_mask:0xc bound_ctrl:1
	v_add_f32_dpp v233, v151, v151 row_mirror row_mask:0xf bank_mask:0x3 bound_ctrl:1
	v_add_f32_dpp v233, v159, v159 row_mirror row_mask:0xf bank_mask:0xc bound_ctrl:1
	v_add_f32_dpp v234, v152, v152 row_mirror row_mask:0xf bank_mask:0x3 bound_ctrl:1
	v_add_f32_dpp v234, v160, v160 row_mirror row_mask:0xf bank_mask:0xc bound_ctrl:1
	v_add_f32_dpp v235, v153, v153 row_mirror row_mask:0xf bank_mask:0x3 bound_ctrl:1
	v_add_f32_dpp v235, v161, v161 row_mirror row_mask:0xf bank_mask:0xc bound_ctrl:1
	v_add_f32_dpp v236, v154, v154 row_mirror row_mask:0xf bank_mask:0x3 bound_ctrl:1
	v_add_f32_dpp v236, v162, v162 row_mirror row_mask:0xf bank_mask:0xc bound_ctrl:1
	v_add_f32_dpp v237, v155, v155 row_mirror row_mask:0xf bank_mask:0x3 bound_ctrl:1
	v_add_f32_dpp v237, v163, v163 row_mirror row_mask:0xf bank_mask:0xc bound_ctrl:1
	v_add_f32_dpp v238, v230, v230 row_half_mirror row_mask:0xf bank_mask:0x5 bound_ctrl:1
	v_add_f32_dpp v238, v234, v234 row_half_mirror row_mask:0xf bank_mask:0xa bound_ctrl:1
	v_add_f32_dpp v239, v231, v231 row_half_mirror row_mask:0xf bank_mask:0x5 bound_ctrl:1
	v_add_f32_dpp v239, v235, v235 row_half_mirror row_mask:0xf bank_mask:0xa bound_ctrl:1
	v_add_f32_dpp v240, v232, v232 row_half_mirror row_mask:0xf bank_mask:0x5 bound_ctrl:1
	v_add_f32_dpp v240, v236, v236 row_half_mirror row_mask:0xf bank_mask:0xa bound_ctrl:1
	v_add_f32_dpp v241, v233, v233 row_half_mirror row_mask:0xf bank_mask:0x5 bound_ctrl:1
	v_add_f32_dpp v241, v237, v237 row_half_mirror row_mask:0xf bank_mask:0xa bound_ctrl:1
	s_mov_b32 vcc_lo, 0xcccccccc
	s_mov_b32 vcc_hi, 0xcccccccc
	v_cndmask_b32 v244, v240, v238, vcc
	v_cndmask_b32 v245, v241, v239, vcc
	v_cndmask_b32 v242, v238, v240, vcc
	v_cndmask_b32 v243, v239, v241, vcc
	v_add_f32_dpp v242, v244, v242 quad_perm:[2,3,0,1] row_mask:0xf bank_mask:0xf bound_ctrl:1
	v_add_f32_dpp v243, v245, v243 quad_perm:[2,3,0,1] row_mask:0xf bank_mask:0xf bound_ctrl:1
	s_mov_b32 vcc_lo, 0xaaaaaaaa
	s_mov_b32 vcc_hi, 0xaaaaaaaa
	v_cndmask_b32 v244, v243, v242, vcc
	v_cndmask_b32 v245, v242, v243, vcc
	s_nop 0
	v_add_f32_dpp v18, v244, v245 quad_perm:[1,0,3,2] row_mask:0xf bank_mask:0xf bound_ctrl:1
	ds_read_b128 v[230:233], v5 offset:29184
	ds_read_b128 v[234:237], v5 offset:29440
	ds_read_b128 v[238:241], v5 offset:29696
	ds_read_b128 v[242:245], v5 offset:29952
	ds_read_b128 v[246:249], v5 offset:30208
	ds_read_b32 v250, v9 offset:29184
	v_add_f32_dpp v146, v146, v146 quad_perm:[1,0,3,2] row_mask:0xf bank_mask:0xf bound_ctrl:1
	v_pk_mul_f32 v[180:181], v[138:139], v[180:181]
	v_pk_fma_f32 v[180:181], v[140:141], v[182:183], v[180:181]
	v_add_f32_dpp v146, v146, v146 quad_perm:[2,3,0,1] row_mask:0xf bank_mask:0xf bound_ctrl:1
	v_add_f32 v148, v180, v181
	v_pk_mul_f32 v[198:199], v[198:199], v[206:207] op_sel_hi:[1,0]
	v_add_f32_dpp v146, v146, v146 row_half_mirror row_mask:0xf bank_mask:0xf bound_ctrl:1
	v_pk_mul_f32 v[200:201], v[200:201], v[206:207] op_sel_hi:[1,0]
	s_waitcnt lgkmcnt(6)
	v_add_f32_dpp v146, v146, v146 row_mirror row_mask:0xf bank_mask:0xf bound_ctrl:1
	v_pk_fma_f32 v[198:199], v[146:147], v[190:191], v[198:199] op_sel_hi:[0,1,1] neg_lo:[1,0,0] neg_hi:[1,0,0]
	v_pk_fma_f32 v[200:201], v[146:147], v[192:193], v[200:201] op_sel_hi:[0,1,1] neg_lo:[1,0,0] neg_hi:[1,0,0]
	v_pk_fma_f32 v[138:139], v[138:139], v[194:195], v[198:199]
	v_pk_fma_f32 v[140:141], v[140:141], v[196:197], v[200:201]
	v_pk_mul_f32 v[144:145], v[138:139], v[208:209]
	v_pk_fma_f32 v[144:145], v[140:141], v[210:211], v[144:145]
	v_add_f32 v146, v144, v145
	ds_read_b128 v[164:167], v5 offset:30720
	ds_read_b128 v[168:171], v5 offset:30976
	ds_read_b128 v[172:175], v5 offset:31232
	ds_read_b128 v[176:179], v5 offset:31488
	ds_read_b128 v[180:183], v5 offset:31744
	ds_read_b32 v184, v9 offset:30720
	v_add_f32_dpp v146, v146, v146 quad_perm:[1,0,3,2] row_mask:0xf bank_mask:0xf bound_ctrl:1
	v_pk_mul_f32 v[202:203], v[138:139], v[202:203]
	v_pk_fma_f32 v[202:203], v[140:141], v[204:205], v[202:203]
	v_add_f32_dpp v146, v146, v146 quad_perm:[2,3,0,1] row_mask:0xf bank_mask:0xf bound_ctrl:1
	v_add_f32 v149, v202, v203
	v_pk_mul_f32 v[220:221], v[220:221], v[228:229] op_sel_hi:[1,0]
	v_add_f32_dpp v146, v146, v146 row_half_mirror row_mask:0xf bank_mask:0xf bound_ctrl:1
	v_pk_mul_f32 v[222:223], v[222:223], v[228:229] op_sel_hi:[1,0]
	s_waitcnt lgkmcnt(6)
	v_add_f32_dpp v146, v146, v146 row_mirror row_mask:0xf bank_mask:0xf bound_ctrl:1
	v_pk_fma_f32 v[220:221], v[146:147], v[212:213], v[220:221] op_sel_hi:[0,1,1] neg_lo:[1,0,0] neg_hi:[1,0,0]
	v_pk_fma_f32 v[222:223], v[146:147], v[214:215], v[222:223] op_sel_hi:[0,1,1] neg_lo:[1,0,0] neg_hi:[1,0,0]
	v_pk_fma_f32 v[138:139], v[138:139], v[216:217], v[220:221]
	v_pk_fma_f32 v[140:141], v[140:141], v[218:219], v[222:223]
	v_pk_mul_f32 v[144:145], v[138:139], v[230:231]
	v_pk_fma_f32 v[144:145], v[140:141], v[232:233], v[144:145]
	v_add_f32 v146, v144, v145
	ds_read_b128 v[186:189], v5 offset:32256
	ds_read_b128 v[190:193], v5 offset:32512
	ds_read_b128 v[194:197], v5 offset:32768
	ds_read_b128 v[198:201], v5 offset:33024
	ds_read_b128 v[202:205], v5 offset:33280
	ds_read_b32 v206, v9 offset:32256
	v_add_f32_dpp v146, v146, v146 quad_perm:[1,0,3,2] row_mask:0xf bank_mask:0xf bound_ctrl:1
	v_pk_mul_f32 v[224:225], v[138:139], v[224:225]
	v_pk_fma_f32 v[224:225], v[140:141], v[226:227], v[224:225]
	v_add_f32_dpp v146, v146, v146 quad_perm:[2,3,0,1] row_mask:0xf bank_mask:0xf bound_ctrl:1
	v_add_f32 v150, v224, v225
	v_pk_mul_f32 v[242:243], v[242:243], v[250:251] op_sel_hi:[1,0]
	v_add_f32_dpp v146, v146, v146 row_half_mirror row_mask:0xf bank_mask:0xf bound_ctrl:1
	v_pk_mul_f32 v[244:245], v[244:245], v[250:251] op_sel_hi:[1,0]
	s_waitcnt lgkmcnt(6)
	v_add_f32_dpp v146, v146, v146 row_mirror row_mask:0xf bank_mask:0xf bound_ctrl:1
	v_pk_fma_f32 v[242:243], v[146:147], v[234:235], v[242:243] op_sel_hi:[0,1,1] neg_lo:[1,0,0] neg_hi:[1,0,0]
	v_pk_fma_f32 v[244:245], v[146:147], v[236:237], v[244:245] op_sel_hi:[0,1,1] neg_lo:[1,0,0] neg_hi:[1,0,0]
	v_pk_fma_f32 v[138:139], v[138:139], v[238:239], v[242:243]
	v_pk_fma_f32 v[140:141], v[140:141], v[240:241], v[244:245]
	v_pk_mul_f32 v[144:145], v[138:139], v[164:165]
	v_pk_fma_f32 v[144:145], v[140:141], v[166:167], v[144:145]
	v_add_f32 v146, v144, v145
	ds_read_b128 v[208:211], v5 offset:33792
	ds_read_b128 v[212:215], v5 offset:34048
	ds_read_b128 v[216:219], v5 offset:34304
	ds_read_b128 v[220:223], v5 offset:34560
	ds_read_b128 v[224:227], v5 offset:34816
	ds_read_b32 v228, v9 offset:33792
	v_add_f32_dpp v146, v146, v146 quad_perm:[1,0,3,2] row_mask:0xf bank_mask:0xf bound_ctrl:1
	v_pk_mul_f32 v[246:247], v[138:139], v[246:247]
	v_pk_fma_f32 v[246:247], v[140:141], v[248:249], v[246:247]
	v_add_f32_dpp v146, v146, v146 quad_perm:[2,3,0,1] row_mask:0xf bank_mask:0xf bound_ctrl:1
	v_add_f32 v151, v246, v247
	v_pk_mul_f32 v[176:177], v[176:177], v[184:185] op_sel_hi:[1,0]
	v_add_f32_dpp v146, v146, v146 row_half_mirror row_mask:0xf bank_mask:0xf bound_ctrl:1
	v_pk_mul_f32 v[178:179], v[178:179], v[184:185] op_sel_hi:[1,0]
	s_waitcnt lgkmcnt(6)
	v_add_f32_dpp v146, v146, v146 row_mirror row_mask:0xf bank_mask:0xf bound_ctrl:1
	v_pk_fma_f32 v[176:177], v[146:147], v[168:169], v[176:177] op_sel_hi:[0,1,1] neg_lo:[1,0,0] neg_hi:[1,0,0]
	v_pk_fma_f32 v[178:179], v[146:147], v[170:171], v[178:179] op_sel_hi:[0,1,1] neg_lo:[1,0,0] neg_hi:[1,0,0]
	v_pk_fma_f32 v[138:139], v[138:139], v[172:173], v[176:177]
	v_pk_fma_f32 v[140:141], v[140:141], v[174:175], v[178:179]
	v_pk_mul_f32 v[144:145], v[138:139], v[186:187]
	v_pk_fma_f32 v[144:145], v[140:141], v[188:189], v[144:145]
	v_add_f32 v146, v144, v145
	ds_read_b128 v[230:233], v5 offset:35328
	ds_read_b128 v[234:237], v5 offset:35584
	ds_read_b128 v[238:241], v5 offset:35840
	ds_read_b128 v[242:245], v5 offset:36096
	ds_read_b128 v[246:249], v5 offset:36352
	ds_read_b32 v250, v9 offset:35328
	v_add_f32_dpp v146, v146, v146 quad_perm:[1,0,3,2] row_mask:0xf bank_mask:0xf bound_ctrl:1
	v_pk_mul_f32 v[180:181], v[138:139], v[180:181]
	v_pk_fma_f32 v[180:181], v[140:141], v[182:183], v[180:181]
	v_add_f32_dpp v146, v146, v146 quad_perm:[2,3,0,1] row_mask:0xf bank_mask:0xf bound_ctrl:1
	v_add_f32 v152, v180, v181
	v_pk_mul_f32 v[198:199], v[198:199], v[206:207] op_sel_hi:[1,0]
	v_add_f32_dpp v146, v146, v146 row_half_mirror row_mask:0xf bank_mask:0xf bound_ctrl:1
	v_pk_mul_f32 v[200:201], v[200:201], v[206:207] op_sel_hi:[1,0]
	s_waitcnt lgkmcnt(6)
	v_add_f32_dpp v146, v146, v146 row_mirror row_mask:0xf bank_mask:0xf bound_ctrl:1
	v_pk_fma_f32 v[198:199], v[146:147], v[190:191], v[198:199] op_sel_hi:[0,1,1] neg_lo:[1,0,0] neg_hi:[1,0,0]
	v_pk_fma_f32 v[200:201], v[146:147], v[192:193], v[200:201] op_sel_hi:[0,1,1] neg_lo:[1,0,0] neg_hi:[1,0,0]
	v_pk_fma_f32 v[138:139], v[138:139], v[194:195], v[198:199]
	v_pk_fma_f32 v[140:141], v[140:141], v[196:197], v[200:201]
	v_pk_mul_f32 v[144:145], v[138:139], v[208:209]
	v_pk_fma_f32 v[144:145], v[140:141], v[210:211], v[144:145]
	v_add_f32 v146, v144, v145
	ds_read_b128 v[164:167], v5 offset:36864
	ds_read_b128 v[168:171], v5 offset:37120
	ds_read_b128 v[172:175], v5 offset:37376
	ds_read_b128 v[176:179], v5 offset:37632
	ds_read_b128 v[180:183], v5 offset:37888
	ds_read_b32 v184, v9 offset:36864
	v_add_f32_dpp v146, v146, v146 quad_perm:[1,0,3,2] row_mask:0xf bank_mask:0xf bound_ctrl:1
	v_pk_mul_f32 v[202:203], v[138:139], v[202:203]
	v_pk_fma_f32 v[202:203], v[140:141], v[204:205], v[202:203]
	v_add_f32_dpp v146, v146, v146 quad_perm:[2,3,0,1] row_mask:0xf bank_mask:0xf bound_ctrl:1
	v_add_f32 v153, v202, v203
	v_pk_mul_f32 v[220:221], v[220:221], v[228:229] op_sel_hi:[1,0]
	v_add_f32_dpp v146, v146, v146 row_half_mirror row_mask:0xf bank_mask:0xf bound_ctrl:1
	v_pk_mul_f32 v[222:223], v[222:223], v[228:229] op_sel_hi:[1,0]
	s_waitcnt lgkmcnt(6)
	v_add_f32_dpp v146, v146, v146 row_mirror row_mask:0xf bank_mask:0xf bound_ctrl:1
	v_pk_fma_f32 v[220:221], v[146:147], v[212:213], v[220:221] op_sel_hi:[0,1,1] neg_lo:[1,0,0] neg_hi:[1,0,0]
	v_pk_fma_f32 v[222:223], v[146:147], v[214:215], v[222:223] op_sel_hi:[0,1,1] neg_lo:[1,0,0] neg_hi:[1,0,0]
	v_pk_fma_f32 v[138:139], v[138:139], v[216:217], v[220:221]
	v_pk_fma_f32 v[140:141], v[140:141], v[218:219], v[222:223]
	v_pk_mul_f32 v[144:145], v[138:139], v[230:231]
	v_pk_fma_f32 v[144:145], v[140:141], v[232:233], v[144:145]
	v_add_f32 v146, v144, v145
	ds_read_b128 v[186:189], v5 offset:38400
	ds_read_b128 v[190:193], v5 offset:38656
	ds_read_b128 v[194:197], v5 offset:38912
	ds_read_b128 v[198:201], v5 offset:39168
	ds_read_b128 v[202:205], v5 offset:39424
	ds_read_b32 v206, v9 offset:38400
	v_add_f32_dpp v146, v146, v146 quad_perm:[1,0,3,2] row_mask:0xf bank_mask:0xf bound_ctrl:1
	v_pk_mul_f32 v[224:225], v[138:139], v[224:225]
	v_pk_fma_f32 v[224:225], v[140:141], v[226:227], v[224:225]
	v_add_f32_dpp v146, v146, v146 quad_perm:[2,3,0,1] row_mask:0xf bank_mask:0xf bound_ctrl:1
	v_add_f32 v154, v224, v225
	v_pk_mul_f32 v[242:243], v[242:243], v[250:251] op_sel_hi:[1,0]
	v_add_f32_dpp v146, v146, v146 row_half_mirror row_mask:0xf bank_mask:0xf bound_ctrl:1
	v_pk_mul_f32 v[244:245], v[244:245], v[250:251] op_sel_hi:[1,0]
	s_waitcnt lgkmcnt(6)
	v_add_f32_dpp v146, v146, v146 row_mirror row_mask:0xf bank_mask:0xf bound_ctrl:1
	v_pk_fma_f32 v[242:243], v[146:147], v[234:235], v[242:243] op_sel_hi:[0,1,1] neg_lo:[1,0,0] neg_hi:[1,0,0]
	v_pk_fma_f32 v[244:245], v[146:147], v[236:237], v[244:245] op_sel_hi:[0,1,1] neg_lo:[1,0,0] neg_hi:[1,0,0]
	v_pk_fma_f32 v[138:139], v[138:139], v[238:239], v[242:243]
	v_pk_fma_f32 v[140:141], v[140:141], v[240:241], v[244:245]
	v_pk_mul_f32 v[144:145], v[138:139], v[164:165]
	v_pk_fma_f32 v[144:145], v[140:141], v[166:167], v[144:145]
	v_add_f32 v146, v144, v145
	ds_read_b128 v[208:211], v5 offset:39936
	ds_read_b128 v[212:215], v5 offset:40192
	ds_read_b128 v[216:219], v5 offset:40448
	ds_read_b128 v[220:223], v5 offset:40704
	ds_read_b128 v[224:227], v5 offset:40960
	ds_read_b32 v228, v9 offset:39936
	v_add_f32_dpp v146, v146, v146 quad_perm:[1,0,3,2] row_mask:0xf bank_mask:0xf bound_ctrl:1
	v_pk_mul_f32 v[246:247], v[138:139], v[246:247]
	v_pk_fma_f32 v[246:247], v[140:141], v[248:249], v[246:247]
	v_add_f32_dpp v146, v146, v146 quad_perm:[2,3,0,1] row_mask:0xf bank_mask:0xf bound_ctrl:1
	v_add_f32 v155, v246, v247
	v_pk_mul_f32 v[176:177], v[176:177], v[184:185] op_sel_hi:[1,0]
	v_add_f32_dpp v146, v146, v146 row_half_mirror row_mask:0xf bank_mask:0xf bound_ctrl:1
	v_pk_mul_f32 v[178:179], v[178:179], v[184:185] op_sel_hi:[1,0]
	s_waitcnt lgkmcnt(6)
	v_add_f32_dpp v146, v146, v146 row_mirror row_mask:0xf bank_mask:0xf bound_ctrl:1
	v_pk_fma_f32 v[176:177], v[146:147], v[168:169], v[176:177] op_sel_hi:[0,1,1] neg_lo:[1,0,0] neg_hi:[1,0,0]
	v_pk_fma_f32 v[178:179], v[146:147], v[170:171], v[178:179] op_sel_hi:[0,1,1] neg_lo:[1,0,0] neg_hi:[1,0,0]
	v_pk_fma_f32 v[138:139], v[138:139], v[172:173], v[176:177]
	v_pk_fma_f32 v[140:141], v[140:141], v[174:175], v[178:179]
	v_pk_mul_f32 v[144:145], v[138:139], v[186:187]
	v_pk_fma_f32 v[144:145], v[140:141], v[188:189], v[144:145]
	v_add_f32 v146, v144, v145
	ds_read_b128 v[230:233], v5 offset:41472
	ds_read_b128 v[234:237], v5 offset:41728
	ds_read_b128 v[238:241], v5 offset:41984
	ds_read_b128 v[242:245], v5 offset:42240
	ds_read_b128 v[246:249], v5 offset:42496
	ds_read_b32 v250, v9 offset:41472
	v_add_f32_dpp v146, v146, v146 quad_perm:[1,0,3,2] row_mask:0xf bank_mask:0xf bound_ctrl:1
	v_pk_mul_f32 v[180:181], v[138:139], v[180:181]
	v_pk_fma_f32 v[180:181], v[140:141], v[182:183], v[180:181]
	v_add_f32_dpp v146, v146, v146 quad_perm:[2,3,0,1] row_mask:0xf bank_mask:0xf bound_ctrl:1
	v_add_f32 v156, v180, v181
	v_pk_mul_f32 v[198:199], v[198:199], v[206:207] op_sel_hi:[1,0]
	v_add_f32_dpp v146, v146, v146 row_half_mirror row_mask:0xf bank_mask:0xf bound_ctrl:1
	v_pk_mul_f32 v[200:201], v[200:201], v[206:207] op_sel_hi:[1,0]
	s_waitcnt lgkmcnt(6)
	v_add_f32_dpp v146, v146, v146 row_mirror row_mask:0xf bank_mask:0xf bound_ctrl:1
	v_pk_fma_f32 v[198:199], v[146:147], v[190:191], v[198:199] op_sel_hi:[0,1,1] neg_lo:[1,0,0] neg_hi:[1,0,0]
	v_pk_fma_f32 v[200:201], v[146:147], v[192:193], v[200:201] op_sel_hi:[0,1,1] neg_lo:[1,0,0] neg_hi:[1,0,0]
	v_pk_fma_f32 v[138:139], v[138:139], v[194:195], v[198:199]
	v_pk_fma_f32 v[140:141], v[140:141], v[196:197], v[200:201]
	v_pk_mul_f32 v[144:145], v[138:139], v[208:209]
	v_pk_fma_f32 v[144:145], v[140:141], v[210:211], v[144:145]
	v_add_f32 v146, v144, v145
	ds_read_b128 v[164:167], v5 offset:43008
	ds_read_b128 v[168:171], v5 offset:43264
	ds_read_b128 v[172:175], v5 offset:43520
	ds_read_b128 v[176:179], v5 offset:43776
	ds_read_b128 v[180:183], v5 offset:44032
	ds_read_b32 v184, v9 offset:43008
	v_add_f32_dpp v146, v146, v146 quad_perm:[1,0,3,2] row_mask:0xf bank_mask:0xf bound_ctrl:1
	v_pk_mul_f32 v[202:203], v[138:139], v[202:203]
	v_pk_fma_f32 v[202:203], v[140:141], v[204:205], v[202:203]
	v_add_f32_dpp v146, v146, v146 quad_perm:[2,3,0,1] row_mask:0xf bank_mask:0xf bound_ctrl:1
	v_add_f32 v157, v202, v203
	v_pk_mul_f32 v[220:221], v[220:221], v[228:229] op_sel_hi:[1,0]
	v_add_f32_dpp v146, v146, v146 row_half_mirror row_mask:0xf bank_mask:0xf bound_ctrl:1
	v_pk_mul_f32 v[222:223], v[222:223], v[228:229] op_sel_hi:[1,0]
	s_waitcnt lgkmcnt(6)
	v_add_f32_dpp v146, v146, v146 row_mirror row_mask:0xf bank_mask:0xf bound_ctrl:1
	v_pk_fma_f32 v[220:221], v[146:147], v[212:213], v[220:221] op_sel_hi:[0,1,1] neg_lo:[1,0,0] neg_hi:[1,0,0]
	v_pk_fma_f32 v[222:223], v[146:147], v[214:215], v[222:223] op_sel_hi:[0,1,1] neg_lo:[1,0,0] neg_hi:[1,0,0]
	v_pk_fma_f32 v[138:139], v[138:139], v[216:217], v[220:221]
	v_pk_fma_f32 v[140:141], v[140:141], v[218:219], v[222:223]
	v_pk_mul_f32 v[144:145], v[138:139], v[230:231]
	v_pk_fma_f32 v[144:145], v[140:141], v[232:233], v[144:145]
	v_add_f32 v146, v144, v145
	ds_read_b128 v[186:189], v5 offset:44544
	ds_read_b128 v[190:193], v5 offset:44800
	ds_read_b128 v[194:197], v5 offset:45056
	ds_read_b128 v[198:201], v5 offset:45312
	ds_read_b128 v[202:205], v5 offset:45568
	ds_read_b32 v206, v9 offset:44544
	v_add_f32_dpp v146, v146, v146 quad_perm:[1,0,3,2] row_mask:0xf bank_mask:0xf bound_ctrl:1
	v_pk_mul_f32 v[224:225], v[138:139], v[224:225]
	v_pk_fma_f32 v[224:225], v[140:141], v[226:227], v[224:225]
	v_add_f32_dpp v146, v146, v146 quad_perm:[2,3,0,1] row_mask:0xf bank_mask:0xf bound_ctrl:1
	v_add_f32 v158, v224, v225
	v_pk_mul_f32 v[242:243], v[242:243], v[250:251] op_sel_hi:[1,0]
	v_add_f32_dpp v146, v146, v146 row_half_mirror row_mask:0xf bank_mask:0xf bound_ctrl:1
	v_pk_mul_f32 v[244:245], v[244:245], v[250:251] op_sel_hi:[1,0]
	s_waitcnt lgkmcnt(6)
	v_add_f32_dpp v146, v146, v146 row_mirror row_mask:0xf bank_mask:0xf bound_ctrl:1
	v_pk_fma_f32 v[242:243], v[146:147], v[234:235], v[242:243] op_sel_hi:[0,1,1] neg_lo:[1,0,0] neg_hi:[1,0,0]
	v_pk_fma_f32 v[244:245], v[146:147], v[236:237], v[244:245] op_sel_hi:[0,1,1] neg_lo:[1,0,0] neg_hi:[1,0,0]
	v_pk_fma_f32 v[138:139], v[138:139], v[238:239], v[242:243]
	v_pk_fma_f32 v[140:141], v[140:141], v[240:241], v[244:245]
	v_pk_mul_f32 v[144:145], v[138:139], v[164:165]
	v_pk_fma_f32 v[144:145], v[140:141], v[166:167], v[144:145]
	v_add_f32 v146, v144, v145
	ds_read_b128 v[208:211], v5 offset:46080
	ds_read_b128 v[212:215], v5 offset:46336
	ds_read_b128 v[216:219], v5 offset:46592
	ds_read_b128 v[220:223], v5 offset:46848
	ds_read_b128 v[224:227], v5 offset:47104
	ds_read_b32 v228, v9 offset:46080
	v_add_f32_dpp v146, v146, v146 quad_perm:[1,0,3,2] row_mask:0xf bank_mask:0xf bound_ctrl:1
	v_pk_mul_f32 v[246:247], v[138:139], v[246:247]
	v_pk_fma_f32 v[246:247], v[140:141], v[248:249], v[246:247]
	v_add_f32_dpp v146, v146, v146 quad_perm:[2,3,0,1] row_mask:0xf bank_mask:0xf bound_ctrl:1
	v_add_f32 v159, v246, v247
	v_pk_mul_f32 v[176:177], v[176:177], v[184:185] op_sel_hi:[1,0]
	v_add_f32_dpp v146, v146, v146 row_half_mirror row_mask:0xf bank_mask:0xf bound_ctrl:1
	v_pk_mul_f32 v[178:179], v[178:179], v[184:185] op_sel_hi:[1,0]
	s_waitcnt lgkmcnt(6)
	v_add_f32_dpp v146, v146, v146 row_mirror row_mask:0xf bank_mask:0xf bound_ctrl:1
	v_pk_fma_f32 v[176:177], v[146:147], v[168:169], v[176:177] op_sel_hi:[0,1,1] neg_lo:[1,0,0] neg_hi:[1,0,0]
	v_pk_fma_f32 v[178:179], v[146:147], v[170:171], v[178:179] op_sel_hi:[0,1,1] neg_lo:[1,0,0] neg_hi:[1,0,0]
	v_pk_fma_f32 v[138:139], v[138:139], v[172:173], v[176:177]
	v_pk_fma_f32 v[140:141], v[140:141], v[174:175], v[178:179]
	v_pk_mul_f32 v[144:145], v[138:139], v[186:187]
	v_pk_fma_f32 v[144:145], v[140:141], v[188:189], v[144:145]
	v_add_f32 v146, v144, v145
	ds_read_b128 v[230:233], v5 offset:47616
	ds_read_b128 v[234:237], v5 offset:47872
	ds_read_b128 v[238:241], v5 offset:48128
	ds_read_b128 v[242:245], v5 offset:48384
	ds_read_b128 v[246:249], v5 offset:48640
	ds_read_b32 v250, v9 offset:47616
	v_add_f32_dpp v146, v146, v146 quad_perm:[1,0,3,2] row_mask:0xf bank_mask:0xf bound_ctrl:1
	v_pk_mul_f32 v[180:181], v[138:139], v[180:181]
	v_pk_fma_f32 v[180:181], v[140:141], v[182:183], v[180:181]
	v_add_f32_dpp v146, v146, v146 quad_perm:[2,3,0,1] row_mask:0xf bank_mask:0xf bound_ctrl:1
	v_add_f32 v160, v180, v181
	v_pk_mul_f32 v[198:199], v[198:199], v[206:207] op_sel_hi:[1,0]
	v_add_f32_dpp v146, v146, v146 row_half_mirror row_mask:0xf bank_mask:0xf bound_ctrl:1
	v_pk_mul_f32 v[200:201], v[200:201], v[206:207] op_sel_hi:[1,0]
	s_waitcnt lgkmcnt(6)
	v_add_f32_dpp v146, v146, v146 row_mirror row_mask:0xf bank_mask:0xf bound_ctrl:1
	v_pk_fma_f32 v[198:199], v[146:147], v[190:191], v[198:199] op_sel_hi:[0,1,1] neg_lo:[1,0,0] neg_hi:[1,0,0]
	v_pk_fma_f32 v[200:201], v[146:147], v[192:193], v[200:201] op_sel_hi:[0,1,1] neg_lo:[1,0,0] neg_hi:[1,0,0]
	v_pk_fma_f32 v[138:139], v[138:139], v[194:195], v[198:199]
	v_pk_fma_f32 v[140:141], v[140:141], v[196:197], v[200:201]
	v_pk_mul_f32 v[144:145], v[138:139], v[208:209]
	v_pk_fma_f32 v[144:145], v[140:141], v[210:211], v[144:145]
	v_add_f32 v146, v144, v145
	s_nop 1
	v_add_f32_dpp v146, v146, v146 quad_perm:[1,0,3,2] row_mask:0xf bank_mask:0xf bound_ctrl:1
	v_pk_mul_f32 v[202:203], v[138:139], v[202:203]
	v_pk_fma_f32 v[202:203], v[140:141], v[204:205], v[202:203]
	v_add_f32_dpp v146, v146, v146 quad_perm:[2,3,0,1] row_mask:0xf bank_mask:0xf bound_ctrl:1
	v_add_f32 v161, v202, v203
	v_pk_mul_f32 v[220:221], v[220:221], v[228:229] op_sel_hi:[1,0]
	v_add_f32_dpp v146, v146, v146 row_half_mirror row_mask:0xf bank_mask:0xf bound_ctrl:1
	v_pk_mul_f32 v[222:223], v[222:223], v[228:229] op_sel_hi:[1,0]
	s_waitcnt lgkmcnt(0)
	v_add_f32_dpp v146, v146, v146 row_mirror row_mask:0xf bank_mask:0xf bound_ctrl:1
	v_pk_fma_f32 v[220:221], v[146:147], v[212:213], v[220:221] op_sel_hi:[0,1,1] neg_lo:[1,0,0] neg_hi:[1,0,0]
	v_pk_fma_f32 v[222:223], v[146:147], v[214:215], v[222:223] op_sel_hi:[0,1,1] neg_lo:[1,0,0] neg_hi:[1,0,0]
	v_pk_fma_f32 v[138:139], v[138:139], v[216:217], v[220:221]
	v_pk_fma_f32 v[140:141], v[140:141], v[218:219], v[222:223]
	v_pk_mul_f32 v[144:145], v[138:139], v[230:231]
	v_pk_fma_f32 v[144:145], v[140:141], v[232:233], v[144:145]
	v_add_f32 v146, v144, v145
	s_nop 1
	v_add_f32_dpp v146, v146, v146 quad_perm:[1,0,3,2] row_mask:0xf bank_mask:0xf bound_ctrl:1
	v_pk_mul_f32 v[224:225], v[138:139], v[224:225]
	v_pk_fma_f32 v[224:225], v[140:141], v[226:227], v[224:225]
	v_add_f32_dpp v146, v146, v146 quad_perm:[2,3,0,1] row_mask:0xf bank_mask:0xf bound_ctrl:1
	v_add_f32 v162, v224, v225
	v_pk_mul_f32 v[242:243], v[242:243], v[250:251] op_sel_hi:[1,0]
	v_add_f32_dpp v146, v146, v146 row_half_mirror row_mask:0xf bank_mask:0xf bound_ctrl:1
	v_pk_mul_f32 v[244:245], v[244:245], v[250:251] op_sel_hi:[1,0]
	s_nop 0
	v_add_f32_dpp v146, v146, v146 row_mirror row_mask:0xf bank_mask:0xf bound_ctrl:1
	v_pk_fma_f32 v[242:243], v[146:147], v[234:235], v[242:243] op_sel_hi:[0,1,1] neg_lo:[1,0,0] neg_hi:[1,0,0]
	v_pk_fma_f32 v[244:245], v[146:147], v[236:237], v[244:245] op_sel_hi:[0,1,1] neg_lo:[1,0,0] neg_hi:[1,0,0]
	v_pk_fma_f32 v[138:139], v[138:139], v[238:239], v[242:243]
	v_pk_fma_f32 v[140:141], v[140:141], v[240:241], v[244:245]
	v_pk_mul_f32 v[246:247], v[138:139], v[246:247]
	v_pk_fma_f32 v[246:247], v[140:141], v[248:249], v[246:247]
	v_add_f32 v163, v246, v247
	s_nop 0
	v_add_f32_dpp v230, v148, v148 row_mirror row_mask:0xf bank_mask:0x3 bound_ctrl:1
	v_add_f32_dpp v230, v156, v156 row_mirror row_mask:0xf bank_mask:0xc bound_ctrl:1
	v_add_f32_dpp v231, v149, v149 row_mirror row_mask:0xf bank_mask:0x3 bound_ctrl:1
	v_add_f32_dpp v231, v157, v157 row_mirror row_mask:0xf bank_mask:0xc bound_ctrl:1
	v_add_f32_dpp v232, v150, v150 row_mirror row_mask:0xf bank_mask:0x3 bound_ctrl:1
	v_add_f32_dpp v232, v158, v158 row_mirror row_mask:0xf bank_mask:0xc bound_ctrl:1
	v_add_f32_dpp v233, v151, v151 row_mirror row_mask:0xf bank_mask:0x3 bound_ctrl:1
	v_add_f32_dpp v233, v159, v159 row_mirror row_mask:0xf bank_mask:0xc bound_ctrl:1
	v_add_f32_dpp v234, v152, v152 row_mirror row_mask:0xf bank_mask:0x3 bound_ctrl:1
	v_add_f32_dpp v234, v160, v160 row_mirror row_mask:0xf bank_mask:0xc bound_ctrl:1
	v_add_f32_dpp v235, v153, v153 row_mirror row_mask:0xf bank_mask:0x3 bound_ctrl:1
	v_add_f32_dpp v235, v161, v161 row_mirror row_mask:0xf bank_mask:0xc bound_ctrl:1
	v_add_f32_dpp v236, v154, v154 row_mirror row_mask:0xf bank_mask:0x3 bound_ctrl:1
	v_add_f32_dpp v236, v162, v162 row_mirror row_mask:0xf bank_mask:0xc bound_ctrl:1
	v_add_f32_dpp v237, v155, v155 row_mirror row_mask:0xf bank_mask:0x3 bound_ctrl:1
	v_add_f32_dpp v237, v163, v163 row_mirror row_mask:0xf bank_mask:0xc bound_ctrl:1
	v_add_f32_dpp v238, v230, v230 row_half_mirror row_mask:0xf bank_mask:0x5 bound_ctrl:1
	v_add_f32_dpp v238, v234, v234 row_half_mirror row_mask:0xf bank_mask:0xa bound_ctrl:1
	v_add_f32_dpp v239, v231, v231 row_half_mirror row_mask:0xf bank_mask:0x5 bound_ctrl:1
	v_add_f32_dpp v239, v235, v235 row_half_mirror row_mask:0xf bank_mask:0xa bound_ctrl:1
	v_add_f32_dpp v240, v232, v232 row_half_mirror row_mask:0xf bank_mask:0x5 bound_ctrl:1
	v_add_f32_dpp v240, v236, v236 row_half_mirror row_mask:0xf bank_mask:0xa bound_ctrl:1
	v_add_f32_dpp v241, v233, v233 row_half_mirror row_mask:0xf bank_mask:0x5 bound_ctrl:1
	v_add_f32_dpp v241, v237, v237 row_half_mirror row_mask:0xf bank_mask:0xa bound_ctrl:1
	s_mov_b32 vcc_lo, 0xcccccccc
	s_mov_b32 vcc_hi, 0xcccccccc
	v_cndmask_b32 v244, v240, v238, vcc
	v_cndmask_b32 v245, v241, v239, vcc
	v_cndmask_b32 v242, v238, v240, vcc
	v_cndmask_b32 v243, v239, v241, vcc
	v_add_f32_dpp v242, v244, v242 quad_perm:[2,3,0,1] row_mask:0xf bank_mask:0xf bound_ctrl:1
	v_add_f32_dpp v243, v245, v243 quad_perm:[2,3,0,1] row_mask:0xf bank_mask:0xf bound_ctrl:1
	s_mov_b32 vcc_lo, 0xaaaaaaaa
	s_mov_b32 vcc_hi, 0xaaaaaaaa
	v_cndmask_b32 v244, v243, v242, vcc
	v_cndmask_b32 v245, v242, v243, vcc
	s_nop 0
	v_add_f32_dpp v19, v244, v245 quad_perm:[1,0,3,2] row_mask:0xf bank_mask:0xf bound_ctrl:1

; #define SCAN_BAR() asm volatile("s_barrier" ::: "memory")
; __device__ __forceinline__ void scan_unit(const Ctx& C0, const float* scn, int T, int quarter, const float* S0, float* Sout, unsigned char* obase, int mode) {
;     ...
;             asm volatile(SCAN_CHUNK_ASM : "+v"(S0x), "+v"(S1x), "+v"(S2x), "+v"(S3x), "=&v"(osel0), "=&v"(osel1) : "v"(aq), "v"(av), "v"(q) : SCAN_CHUNK_CLOBBERS, "memory");
;             if (mode == 0) { *(float*)(obase + (size_t)(k * 32 + q) * UPITCH_B + rl * 4) = osel0; *(float*)(obase + (size_t)(k * 32 + 16 + q) * UPITCH_B + rl * 4) = osel1; }
;             SCAN_BAR();
;         }
	s_barrier
	ds_read_b128 v[164:167], v10 offset:0
	ds_read_b128 v[168:171], v10 offset:256
	ds_read_b128 v[172:175], v10 offset:512
	ds_read_b128 v[176:179], v10 offset:768
	ds_read_b128 v[180:183], v10 offset:1024
	ds_read_b32 v184, v11 offset:0
	ds_read_b128 v[186:189], v10 offset:1536
	ds_read_b128 v[190:193], v10 offset:1792
	ds_read_b128 v[194:197], v10 offset:2048
	ds_read_b128 v[198:201], v10 offset:2304
	ds_read_b128 v[202:205], v10 offset:2560
	ds_read_b32 v206, v11 offset:1536
	v_lshl_add_u64 v[14:15], v[6:7], 0, s[0:1]
	v_add_co_u32_e32 v16, vcc, 0xfc29000, v14
	s_mov_b32 s8, 0xfc7f000
	s_nop 0
	v_addc_co_u32_e32 v17, vcc, 0, v15, vcc
	global_store_dword v[16:17], v18, off offset:768
	v_add_co_u32_e32 v16, vcc, 0xfc54000, v14
	s_add_u32 s0, s0, 0xac000
	s_nop 0
	v_addc_co_u32_e32 v17, vcc, 0, v15, vcc
	global_store_dword v[16:17], v19, off offset:768
	s_waitcnt lgkmcnt(6)
	v_pk_mul_f32 v[144:145], v[138:139], v[164:165]
	v_pk_fma_f32 v[144:145], v[140:141], v[166:167], v[144:145]
	v_add_f32 v146, v144, v145
	ds_read_b128 v[208:211], v10 offset:3072
	ds_read_b128 v[212:215], v10 offset:3328
	ds_read_b128 v[216:219], v10 offset:3584
	ds_read_b128 v[220:223], v10 offset:3840
	ds_read_b128 v[224:227], v10 offset:4096
	ds_read_b32 v228, v11 offset:3072
	v_add_f32_dpp v146, v146, v146 quad_perm:[1,0,3,2] row_mask:0xf bank_mask:0xf bound_ctrl:1
	s_nop 0
	s_nop 0
	v_add_f32_dpp v146, v146, v146 quad_perm:[2,3,0,1] row_mask:0xf bank_mask:0xf bound_ctrl:1
	s_nop 0
	v_pk_mul_f32 v[176:177], v[176:177], v[184:185] op_sel_hi:[1,0]
	v_add_f32_dpp v146, v146, v146 row_half_mirror row_mask:0xf bank_mask:0xf bound_ctrl:1
	v_pk_mul_f32 v[178:179], v[178:179], v[184:185] op_sel_hi:[1,0]
	s_waitcnt lgkmcnt(6)
	v_add_f32_dpp v146, v146, v146 row_mirror row_mask:0xf bank_mask:0xf bound_ctrl:1
	v_pk_fma_f32 v[176:177], v[146:147], v[168:169], v[176:177] op_sel_hi:[0,1,1] neg_lo:[1,0,0] neg_hi:[1,0,0]
	v_pk_fma_f32 v[178:179], v[146:147], v[170:171], v[178:179] op_sel_hi:[0,1,1] neg_lo:[1,0,0] neg_hi:[1,0,0]
	v_pk_fma_f32 v[138:139], v[138:139], v[172:173], v[176:177]
	v_pk_fma_f32 v[140:141], v[140:141], v[174:175], v[178:179]
	v_pk_mul_f32 v[144:145], v[138:139], v[186:187]
	v_pk_fma_f32 v[144:145], v[140:141], v[188:189], v[144:145]
	v_add_f32 v146, v144, v145
	ds_read_b128 v[230:233], v10 offset:4608
	ds_read_b128 v[234:237], v10 offset:4864
	ds_read_b128 v[238:241], v10 offset:5120
	ds_read_b128 v[242:245], v10 offset:5376
	ds_read_b128 v[246:249], v10 offset:5632
	ds_read_b32 v250, v11 offset:4608
	v_add_f32_dpp v146, v146, v146 quad_perm:[1,0,3,2] row_mask:0xf bank_mask:0xf bound_ctrl:1
	v_pk_mul_f32 v[180:181], v[138:139], v[180:181]
	v_pk_fma_f32 v[180:181], v[140:141], v[182:183], v[180:181]
	v_add_f32_dpp v146, v146, v146 quad_perm:[2,3,0,1] row_mask:0xf bank_mask:0xf bound_ctrl:1
	v_add_f32 v148, v180, v181
	v_pk_mul_f32 v[198:199], v[198:199], v[206:207] op_sel_hi:[1,0]
	v_add_f32_dpp v146, v146, v146 row_half_mirror row_mask:0xf bank_mask:0xf bound_ctrl:1
	v_pk_mul_f32 v[200:201], v[200:201], v[206:207] op_sel_hi:[1,0]
	s_waitcnt lgkmcnt(6)
	v_add_f32_dpp v146, v146, v146 row_mirror row_mask:0xf bank_mask:0xf bound_ctrl:1
	v_pk_fma_f32 v[198:199], v[146:147], v[190:191], v[198:199] op_sel_hi:[0,1,1] neg_lo:[1,0,0] neg_hi:[1,0,0]
	v_pk_fma_f32 v[200:201], v[146:147], v[192:193], v[200:201] op_sel_hi:[0,1,1] neg_lo:[1,0,0] neg_hi:[1,0,0]
	v_pk_fma_f32 v[138:139], v[138:139], v[194:195], v[198:199]
	v_pk_fma_f32 v[140:141], v[140:141], v[196:197], v[200:201]
	v_pk_mul_f32 v[144:145], v[138:139], v[208:209]
	v_pk_fma_f32 v[144:145], v[140:141], v[210:211], v[144:145]
	v_add_f32 v146, v144, v145
	ds_read_b128 v[164:167], v10 offset:6144
	ds_read_b128 v[168:171], v10 offset:6400
	ds_read_b128 v[172:175], v10 offset:6656
	ds_read_b128 v[176:179], v10 offset:6912
	ds_read_b128 v[180:183], v10 offset:7168
	ds_read_b32 v184, v11 offset:6144
	v_add_f32_dpp v146, v146, v146 quad_perm:[1,0,3,2] row_mask:0xf bank_mask:0xf bound_ctrl:1
	v_pk_mul_f32 v[202:203], v[138:139], v[202:203]
	v_pk_fma_f32 v[202:203], v[140:141], v[204:205], v[202:203]
	v_add_f32_dpp v146, v146, v146 quad_perm:[2,3,0,1] row_mask:0xf bank_mask:0xf bound_ctrl:1
	v_add_f32 v149, v202, v203
	v_pk_mul_f32 v[220:221], v[220:221], v[228:229] op_sel_hi:[1,0]
	v_add_f32_dpp v146, v146, v146 row_half_mirror row_mask:0xf bank_mask:0xf bound_ctrl:1
	v_pk_mul_f32 v[222:223], v[222:223], v[228:229] op_sel_hi:[1,0]
	s_waitcnt lgkmcnt(6)
	v_add_f32_dpp v146, v146, v146 row_mirror row_mask:0xf bank_mask:0xf bound_ctrl:1
	v_pk_fma_f32 v[220:221], v[146:147], v[212:213], v[220:221] op_sel_hi:[0,1,1] neg_lo:[1,0,0] neg_hi:[1,0,0]
	v_pk_fma_f32 v[222:223], v[146:147], v[214:215], v[222:223] op_sel_hi:[0,1,1] neg_lo:[1,0,0] neg_hi:[1,0,0]
	v_pk_fma_f32 v[138:139], v[138:139], v[216:217], v[220:221]
	v_pk_fma_f32 v[140:141], v[140:141], v[218:219], v[222:223]
	v_pk_mul_f32 v[144:145], v[138:139], v[230:231]
	v_pk_fma_f32 v[144:145], v[140:141], v[232:233], v[144:145]
	v_add_f32 v146, v144, v145
	ds_read_b128 v[186:189], v10 offset:7680
	ds_read_b128 v[190:193], v10 offset:7936
	ds_read_b128 v[194:197], v10 offset:8192
	ds_read_b128 v[198:201], v10 offset:8448
	ds_read_b128 v[202:205], v10 offset:8704
	ds_read_b32 v206, v11 offset:7680
	v_add_f32_dpp v146, v146, v146 quad_perm:[1,0,3,2] row_mask:0xf bank_mask:0xf bound_ctrl:1
	v_pk_mul_f32 v[224:225], v[138:139], v[224:225]
	v_pk_fma_f32 v[224:225], v[140:141], v[226:227], v[224:225]
	v_add_f32_dpp v146, v146, v146 quad_perm:[2,3,0,1] row_mask:0xf bank_mask:0xf bound_ctrl:1
	v_add_f32 v150, v224, v225
	v_pk_mul_f32 v[242:243], v[242:243], v[250:251] op_sel_hi:[1,0]
	v_add_f32_dpp v146, v146, v146 row_half_mirror row_mask:0xf bank_mask:0xf bound_ctrl:1
	v_pk_mul_f32 v[244:245], v[244:245], v[250:251] op_sel_hi:[1,0]
	s_waitcnt lgkmcnt(6)
	v_add_f32_dpp v146, v146, v146 row_mirror row_mask:0xf bank_mask:0xf bound_ctrl:1
	v_pk_fma_f32 v[242:243], v[146:147], v[234:235], v[242:243] op_sel_hi:[0,1,1] neg_lo:[1,0,0] neg_hi:[1,0,0]
	v_pk_fma_f32 v[244:245], v[146:147], v[236:237], v[244:245] op_sel_hi:[0,1,1] neg_lo:[1,0,0] neg_hi:[1,0,0]
	v_pk_fma_f32 v[138:139], v[138:139], v[238:239], v[242:243]
	v_pk_fma_f32 v[140:141], v[140:141], v[240:241], v[244:245]
	v_pk_mul_f32 v[144:145], v[138:139], v[164:165]
	v_pk_fma_f32 v[144:145], v[140:141], v[166:167], v[144:145]
	v_add_f32 v146, v144, v145
	ds_read_b128 v[208:211], v10 offset:9216
	ds_read_b128 v[212:215], v10 offset:9472
	ds_read_b128 v[216:219], v10 offset:9728
	ds_read_b128 v[220:223], v10 offset:9984
	ds_read_b128 v[224:227], v10 offset:10240
	ds_read_b32 v228, v11 offset:9216
	v_add_f32_dpp v146, v146, v146 quad_perm:[1,0,3,2] row_mask:0xf bank_mask:0xf bound_ctrl:1
	v_pk_mul_f32 v[246:247], v[138:139], v[246:247]
	v_pk_fma_f32 v[246:247], v[140:141], v[248:249], v[246:247]
	v_add_f32_dpp v146, v146, v146 quad_perm:[2,3,0,1] row_mask:0xf bank_mask:0xf bound_ctrl:1
	v_add_f32 v151, v246, v247
	v_pk_mul_f32 v[176:177], v[176:177], v[184:185] op_sel_hi:[1,0]
	v_add_f32_dpp v146, v146, v146 row_half_mirror row_mask:0xf bank_mask:0xf bound_ctrl:1
	v_pk_mul_f32 v[178:179], v[178:179], v[184:185] op_sel_hi:[1,0]
	s_waitcnt lgkmcnt(6)
	v_add_f32_dpp v146, v146, v146 row_mirror row_mask:0xf bank_mask:0xf bound_ctrl:1
	v_pk_fma_f32 v[176:177], v[146:147], v[168:169], v[176:177] op_sel_hi:[0,1,1] neg_lo:[1,0,0] neg_hi:[1,0,0]
	v_pk_fma_f32 v[178:179], v[146:147], v[170:171], v[178:179] op_sel_hi:[0,1,1] neg_lo:[1,0,0] neg_hi:[1,0,0]
	v_pk_fma_f32 v[138:139], v[138:139], v[172:173], v[176:177]
	v_pk_fma_f32 v[140:141], v[140:141], v[174:175], v[178:179]
	v_pk_mul_f32 v[144:145], v[138:139], v[186:187]
	v_pk_fma_f32 v[144:145], v[140:141], v[188:189], v[144:145]
	v_add_f32 v146, v144, v145
	ds_read_b128 v[230:233], v10 offset:10752
	ds_read_b128 v[234:237], v10 offset:11008
	ds_read_b128 v[238:241], v10 offset:11264
	ds_read_b128 v[242:245], v10 offset:11520
	ds_read_b128 v[246:249], v10 offset:11776
	ds_read_b32 v250, v11 offset:10752
	v_add_f32_dpp v146, v146, v146 quad_perm:[1,0,3,2] row_mask:0xf bank_mask:0xf bound_ctrl:1
	v_pk_mul_f32 v[180:181], v[138:139], v[180:181]
	v_pk_fma_f32 v[180:181], v[140:141], v[182:183], v[180:181]
	v_add_f32_dpp v146, v146, v146 quad_perm:[2,3,0,1] row_mask:0xf bank_mask:0xf bound_ctrl:1
	v_add_f32 v152, v180, v181
	v_pk_mul_f32 v[198:199], v[198:199], v[206:207] op_sel_hi:[1,0]
	v_add_f32_dpp v146, v146, v146 row_half_mirror row_mask:0xf bank_mask:0xf bound_ctrl:1
	v_pk_mul_f32 v[200:201], v[200:201], v[206:207] op_sel_hi:[1,0]
	s_waitcnt lgkmcnt(6)
	v_add_f32_dpp v146, v146, v146 row_mirror row_mask:0xf bank_mask:0xf bound_ctrl:1
	v_pk_fma_f32 v[198:199], v[146:147], v[190:191], v[198:199] op_sel_hi:[0,1,1] neg_lo:[1,0,0] neg_hi:[1,0,0]
	v_pk_fma_f32 v[200:201], v[146:147], v[192:193], v[200:201] op_sel_hi:[0,1,1] neg_lo:[1,0,0] neg_hi:[1,0,0]
	v_pk_fma_f32 v[138:139], v[138:139], v[194:195], v[198:199]
	v_pk_fma_f32 v[140:141], v[140:141], v[196:197], v[200:201]
	v_pk_mul_f32 v[144:145], v[138:139], v[208:209]
	v_pk_fma_f32 v[144:145], v[140:141], v[210:211], v[144:145]
	v_add_f32 v146, v144, v145
	ds_read_b128 v[164:167], v10 offset:12288
	ds_read_b128 v[168:171], v10 offset:12544
	ds_read_b128 v[172:175], v10 offset:12800
	ds_read_b128 v[176:179], v10 offset:13056
	ds_read_b128 v[180:183], v10 offset:13312
	ds_read_b32 v184, v11 offset:12288
	v_add_f32_dpp v146, v146, v146 quad_perm:[1,0,3,2] row_mask:0xf bank_mask:0xf bound_ctrl:1
	v_pk_mul_f32 v[202:203], v[138:139], v[202:203]
	v_pk_fma_f32 v[202:203], v[140:141], v[204:205], v[202:203]
	v_add_f32_dpp v146, v146, v146 quad_perm:[2,3,0,1] row_mask:0xf bank_mask:0xf bound_ctrl:1
	v_add_f32 v153, v202, v203
	v_pk_mul_f32 v[220:221], v[220:221], v[228:229] op_sel_hi:[1,0]
	v_add_f32_dpp v146, v146, v146 row_half_mirror row_mask:0xf bank_mask:0xf bound_ctrl:1
	v_pk_mul_f32 v[222:223], v[222:223], v[228:229] op_sel_hi:[1,0]
	s_waitcnt lgkmcnt(6)
	v_add_f32_dpp v146, v146, v146 row_mirror row_mask:0xf bank_mask:0xf bound_ctrl:1
	v_pk_fma_f32 v[220:221], v[146:147], v[212:213], v[220:221] op_sel_hi:[0,1,1] neg_lo:[1,0,0] neg_hi:[1,0,0]
	v_pk_fma_f32 v[222:223], v[146:147], v[214:215], v[222:223] op_sel_hi:[0,1,1] neg_lo:[1,0,0] neg_hi:[1,0,0]
	v_pk_fma_f32 v[138:139], v[138:139], v[216:217], v[220:221]
	v_pk_fma_f32 v[140:141], v[140:141], v[218:219], v[222:223]
	v_pk_mul_f32 v[144:145], v[138:139], v[230:231]
	v_pk_fma_f32 v[144:145], v[140:141], v[232:233], v[144:145]
	v_add_f32 v146, v144, v145
	ds_read_b128 v[186:189], v10 offset:13824
	ds_read_b128 v[190:193], v10 offset:14080
	ds_read_b128 v[194:197], v10 offset:14336
	ds_read_b128 v[198:201], v10 offset:14592
	ds_read_b128 v[202:205], v10 offset:14848
	ds_read_b32 v206, v11 offset:13824
	v_add_f32_dpp v146, v146, v146 quad_perm:[1,0,3,2] row_mask:0xf bank_mask:0xf bound_ctrl:1
	v_pk_mul_f32 v[224:225], v[138:139], v[224:225]
	v_pk_fma_f32 v[224:225], v[140:141], v[226:227], v[224:225]
	v_add_f32_dpp v146, v146, v146 quad_perm:[2,3,0,1] row_mask:0xf bank_mask:0xf bound_ctrl:1
	v_add_f32 v154, v224, v225
	v_pk_mul_f32 v[242:243], v[242:243], v[250:251] op_sel_hi:[1,0]
	v_add_f32_dpp v146, v146, v146 row_half_mirror row_mask:0xf bank_mask:0xf bound_ctrl:1
	v_pk_mul_f32 v[244:245], v[244:245], v[250:251] op_sel_hi:[1,0]
	s_waitcnt lgkmcnt(6)
	v_add_f32_dpp v146, v146, v146 row_mirror row_mask:0xf bank_mask:0xf bound_ctrl:1
	v_pk_fma_f32 v[242:243], v[146:147], v[234:235], v[242:243] op_sel_hi:[0,1,1] neg_lo:[1,0,0] neg_hi:[1,0,0]
	v_pk_fma_f32 v[244:245], v[146:147], v[236:237], v[244:245] op_sel_hi:[0,1,1] neg_lo:[1,0,0] neg_hi:[1,0,0]
	v_pk_fma_f32 v[138:139], v[138:139], v[238:239], v[242:243]
	v_pk_fma_f32 v[140:141], v[140:141], v[240:241], v[244:245]
	v_pk_mul_f32 v[144:145], v[138:139], v[164:165]
	v_pk_fma_f32 v[144:145], v[140:141], v[166:167], v[144:145]
	v_add_f32 v146, v144, v145
	ds_read_b128 v[208:211], v10 offset:15360
	ds_read_b128 v[212:215], v10 offset:15616
	ds_read_b128 v[216:219], v10 offset:15872
	ds_read_b128 v[220:223], v10 offset:16128
	ds_read_b128 v[224:227], v10 offset:16384
	ds_read_b32 v228, v11 offset:15360
	v_add_f32_dpp v146, v146, v146 quad_perm:[1,0,3,2] row_mask:0xf bank_mask:0xf bound_ctrl:1
	v_pk_mul_f32 v[246:247], v[138:139], v[246:247]
	v_pk_fma_f32 v[246:247], v[140:141], v[248:249], v[246:247]
	v_add_f32_dpp v146, v146, v146 quad_perm:[2,3,0,1] row_mask:0xf bank_mask:0xf bound_ctrl:1
	v_add_f32 v155, v246, v247
	v_pk_mul_f32 v[176:177], v[176:177], v[184:185] op_sel_hi:[1,0]
	v_add_f32_dpp v146, v146, v146 row_half_mirror row_mask:0xf bank_mask:0xf bound_ctrl:1
	v_pk_mul_f32 v[178:179], v[178:179], v[184:185] op_sel_hi:[1,0]
	s_waitcnt lgkmcnt(6)
	v_add_f32_dpp v146, v146, v146 row_mirror row_mask:0xf bank_mask:0xf bound_ctrl:1
	v_pk_fma_f32 v[176:177], v[146:147], v[168:169], v[176:177] op_sel_hi:[0,1,1] neg_lo:[1,0,0] neg_hi:[1,0,0]
	v_pk_fma_f32 v[178:179], v[146:147], v[170:171], v[178:179] op_sel_hi:[0,1,1] neg_lo:[1,0,0] neg_hi:[1,0,0]
	v_pk_fma_f32 v[138:139], v[138:139], v[172:173], v[176:177]
	v_pk_fma_f32 v[140:141], v[140:141], v[174:175], v[178:179]
	v_pk_mul_f32 v[144:145], v[138:139], v[186:187]
	v_pk_fma_f32 v[144:145], v[140:141], v[188:189], v[144:145]
	v_add_f32 v146, v144, v145
	ds_read_b128 v[230:233], v10 offset:16896
	ds_read_b128 v[234:237], v10 offset:17152
	ds_read_b128 v[238:241], v10 offset:17408
	ds_read_b128 v[242:245], v10 offset:17664
	ds_read_b128 v[246:249], v10 offset:17920
	ds_read_b32 v250, v11 offset:16896
	v_add_f32_dpp v146, v146, v146 quad_perm:[1,0,3,2] row_mask:0xf bank_mask:0xf bound_ctrl:1
	v_pk_mul_f32 v[180:181], v[138:139], v[180:181]
	v_pk_fma_f32 v[180:181], v[140:141], v[182:183], v[180:181]
	v_add_f32_dpp v146, v146, v146 quad_perm:[2,3,0,1] row_mask:0xf bank_mask:0xf bound_ctrl:1
	v_add_f32 v156, v180, v181
	v_pk_mul_f32 v[198:199], v[198:199], v[206:207] op_sel_hi:[1,0]
	v_add_f32_dpp v146, v146, v146 row_half_mirror row_mask:0xf bank_mask:0xf bound_ctrl:1
	v_pk_mul_f32 v[200:201], v[200:201], v[206:207] op_sel_hi:[1,0]
	s_waitcnt lgkmcnt(6)
	v_add_f32_dpp v146, v146, v146 row_mirror row_mask:0xf bank_mask:0xf bound_ctrl:1
	v_pk_fma_f32 v[198:199], v[146:147], v[190:191], v[198:199] op_sel_hi:[0,1,1] neg_lo:[1,0,0] neg_hi:[1,0,0]
	v_pk_fma_f32 v[200:201], v[146:147], v[192:193], v[200:201] op_sel_hi:[0,1,1] neg_lo:[1,0,0] neg_hi:[1,0,0]
	v_pk_fma_f32 v[138:139], v[138:139], v[194:195], v[198:199]
	v_pk_fma_f32 v[140:141], v[140:141], v[196:197], v[200:201]
	v_pk_mul_f32 v[144:145], v[138:139], v[208:209]
	v_pk_fma_f32 v[144:145], v[140:141], v[210:211], v[144:145]
	v_add_f32 v146, v144, v145
	ds_read_b128 v[164:167], v10 offset:18432
	ds_read_b128 v[168:171], v10 offset:18688
	ds_read_b128 v[172:175], v10 offset:18944
	ds_read_b128 v[176:179], v10 offset:19200
	ds_read_b128 v[180:183], v10 offset:19456
	ds_read_b32 v184, v11 offset:18432
	v_add_f32_dpp v146, v146, v146 quad_perm:[1,0,3,2] row_mask:0xf bank_mask:0xf bound_ctrl:1
	v_pk_mul_f32 v[202:203], v[138:139], v[202:203]
	v_pk_fma_f32 v[202:203], v[140:141], v[204:205], v[202:203]
	v_add_f32_dpp v146, v146, v146 quad_perm:[2,3,0,1] row_mask:0xf bank_mask:0xf bound_ctrl:1
	v_add_f32 v157, v202, v203
	v_pk_mul_f32 v[220:221], v[220:221], v[228:229] op_sel_hi:[1,0]
	v_add_f32_dpp v146, v146, v146 row_half_mirror row_mask:0xf bank_mask:0xf bound_ctrl:1
	v_pk_mul_f32 v[222:223], v[222:223], v[228:229] op_sel_hi:[1,0]
	s_waitcnt lgkmcnt(6)
	v_add_f32_dpp v146, v146, v146 row_mirror row_mask:0xf bank_mask:0xf bound_ctrl:1
	v_pk_fma_f32 v[220:221], v[146:147], v[212:213], v[220:221] op_sel_hi:[0,1,1] neg_lo:[1,0,0] neg_hi:[1,0,0]
	v_pk_fma_f32 v[222:223], v[146:147], v[214:215], v[222:223] op_sel_hi:[0,1,1] neg_lo:[1,0,0] neg_hi:[1,0,0]
	v_pk_fma_f32 v[138:139], v[138:139], v[216:217], v[220:221]
	v_pk_fma_f32 v[140:141], v[140:141], v[218:219], v[222:223]
	v_pk_mul_f32 v[144:145], v[138:139], v[230:231]
	v_pk_fma_f32 v[144:145], v[140:141], v[232:233], v[144:145]
	v_add_f32 v146, v144, v145
	ds_read_b128 v[186:189], v10 offset:19968
	ds_read_b128 v[190:193], v10 offset:20224
	ds_read_b128 v[194:197], v10 offset:20480
	ds_read_b128 v[198:201], v10 offset:20736
	ds_read_b128 v[202:205], v10 offset:20992
	ds_read_b32 v206, v11 offset:19968
	v_add_f32_dpp v146, v146, v146 quad_perm:[1,0,3,2] row_mask:0xf bank_mask:0xf bound_ctrl:1
	v_pk_mul_f32 v[224:225], v[138:139], v[224:225]
	v_pk_fma_f32 v[224:225], v[140:141], v[226:227], v[224:225]
	v_add_f32_dpp v146, v146, v146 quad_perm:[2,3,0,1] row_mask:0xf bank_mask:0xf bound_ctrl:1
	v_add_f32 v158, v224, v225
	v_pk_mul_f32 v[242:243], v[242:243], v[250:251] op_sel_hi:[1,0]
	v_add_f32_dpp v146, v146, v146 row_half_mirror row_mask:0xf bank_mask:0xf bound_ctrl:1
	v_pk_mul_f32 v[244:245], v[244:245], v[250:251] op_sel_hi:[1,0]
	s_waitcnt lgkmcnt(6)
	v_add_f32_dpp v146, v146, v146 row_mirror row_mask:0xf bank_mask:0xf bound_ctrl:1
	v_pk_fma_f32 v[242:243], v[146:147], v[234:235], v[242:243] op_sel_hi:[0,1,1] neg_lo:[1,0,0] neg_hi:[1,0,0]
	v_pk_fma_f32 v[244:245], v[146:147], v[236:237], v[244:245] op_sel_hi:[0,1,1] neg_lo:[1,0,0] neg_hi:[1,0,0]
	v_pk_fma_f32 v[138:139], v[138:139], v[238:239], v[242:243]
	v_pk_fma_f32 v[140:141], v[140:141], v[240:241], v[244:245]
	v_pk_mul_f32 v[144:145], v[138:139], v[164:165]
	v_pk_fma_f32 v[144:145], v[140:141], v[166:167], v[144:145]
	v_add_f32 v146, v144, v145
	ds_read_b128 v[208:211], v10 offset:21504
	ds_read_b128 v[212:215], v10 offset:21760
	ds_read_b128 v[216:219], v10 offset:22016
	ds_read_b128 v[220:223], v10 offset:22272
	ds_read_b128 v[224:227], v10 offset:22528
	ds_read_b32 v228, v11 offset:21504
	v_add_f32_dpp v146, v146, v146 quad_perm:[1,0,3,2] row_mask:0xf bank_mask:0xf bound_ctrl:1
	v_pk_mul_f32 v[246:247], v[138:139], v[246:247]
	v_pk_fma_f32 v[246:247], v[140:141], v[248:249], v[246:247]
	v_add_f32_dpp v146, v146, v146 quad_perm:[2,3,0,1] row_mask:0xf bank_mask:0xf bound_ctrl:1
	v_add_f32 v159, v246, v247
	v_pk_mul_f32 v[176:177], v[176:177], v[184:185] op_sel_hi:[1,0]
	v_add_f32_dpp v146, v146, v146 row_half_mirror row_mask:0xf bank_mask:0xf bound_ctrl:1
	v_pk_mul_f32 v[178:179], v[178:179], v[184:185] op_sel_hi:[1,0]
	s_waitcnt lgkmcnt(6)
	v_add_f32_dpp v146, v146, v146 row_mirror row_mask:0xf bank_mask:0xf bound_ctrl:1
	v_pk_fma_f32 v[176:177], v[146:147], v[168:169], v[176:177] op_sel_hi:[0,1,1] neg_lo:[1,0,0] neg_hi:[1,0,0]
	v_pk_fma_f32 v[178:179], v[146:147], v[170:171], v[178:179] op_sel_hi:[0,1,1] neg_lo:[1,0,0] neg_hi:[1,0,0]
	v_pk_fma_f32 v[138:139], v[138:139], v[172:173], v[176:177]
	v_pk_fma_f32 v[140:141], v[140:141], v[174:175], v[178:179]
	v_pk_mul_f32 v[144:145], v[138:139], v[186:187]
	v_pk_fma_f32 v[144:145], v[140:141], v[188:189], v[144:145]
	v_add_f32 v146, v144, v145
	ds_read_b128 v[230:233], v10 offset:23040
	ds_read_b128 v[234:237], v10 offset:23296
	ds_read_b128 v[238:241], v10 offset:23552
	ds_read_b128 v[242:245], v10 offset:23808
	ds_read_b128 v[246:249], v10 offset:24064
	ds_read_b32 v250, v11 offset:23040
	v_add_f32_dpp v146, v146, v146 quad_perm:[1,0,3,2] row_mask:0xf bank_mask:0xf bound_ctrl:1
	v_pk_mul_f32 v[180:181], v[138:139], v[180:181]
	v_pk_fma_f32 v[180:181], v[140:141], v[182:183], v[180:181]
	v_add_f32_dpp v146, v146, v146 quad_perm:[2,3,0,1] row_mask:0xf bank_mask:0xf bound_ctrl:1
	v_add_f32 v160, v180, v181
	v_pk_mul_f32 v[198:199], v[198:199], v[206:207] op_sel_hi:[1,0]
	v_add_f32_dpp v146, v146, v146 row_half_mirror row_mask:0xf bank_mask:0xf bound_ctrl:1
	v_pk_mul_f32 v[200:201], v[200:201], v[206:207] op_sel_hi:[1,0]
	s_waitcnt lgkmcnt(6)
	v_add_f32_dpp v146, v146, v146 row_mirror row_mask:0xf bank_mask:0xf bound_ctrl:1
	v_pk_fma_f32 v[198:199], v[146:147], v[190:191], v[198:199] op_sel_hi:[0,1,1] neg_lo:[1,0,0] neg_hi:[1,0,0]
	v_pk_fma_f32 v[200:201], v[146:147], v[192:193], v[200:201] op_sel_hi:[0,1,1] neg_lo:[1,0,0] neg_hi:[1,0,0]
	v_pk_fma_f32 v[138:139], v[138:139], v[194:195], v[198:199]
	v_pk_fma_f32 v[140:141], v[140:141], v[196:197], v[200:201]
	v_pk_mul_f32 v[144:145], v[138:139], v[208:209]
	v_pk_fma_f32 v[144:145], v[140:141], v[210:211], v[144:145]
	v_add_f32 v146, v144, v145
	ds_read_b128 v[164:167], v10 offset:24576
	ds_read_b128 v[168:171], v10 offset:24832
	ds_read_b128 v[172:175], v10 offset:25088
	ds_read_b128 v[176:179], v10 offset:25344
	ds_read_b128 v[180:183], v10 offset:25600
	ds_read_b32 v184, v11 offset:24576
	v_add_f32_dpp v146, v146, v146 quad_perm:[1,0,3,2] row_mask:0xf bank_mask:0xf bound_ctrl:1
	v_pk_mul_f32 v[202:203], v[138:139], v[202:203]
	v_pk_fma_f32 v[202:203], v[140:141], v[204:205], v[202:203]
	v_add_f32_dpp v146, v146, v146 quad_perm:[2,3,0,1] row_mask:0xf bank_mask:0xf bound_ctrl:1
	v_add_f32 v161, v202, v203
	v_pk_mul_f32 v[220:221], v[220:221], v[228:229] op_sel_hi:[1,0]
	v_add_f32_dpp v146, v146, v146 row_half_mirror row_mask:0xf bank_mask:0xf bound_ctrl:1
	v_pk_mul_f32 v[222:223], v[222:223], v[228:229] op_sel_hi:[1,0]
	s_waitcnt lgkmcnt(6)
	v_add_f32_dpp v146, v146, v146 row_mirror row_mask:0xf bank_mask:0xf bound_ctrl:1
	v_pk_fma_f32 v[220:221], v[146:147], v[212:213], v[220:221] op_sel_hi:[0,1,1] neg_lo:[1,0,0] neg_hi:[1,0,0]
	v_pk_fma_f32 v[222:223], v[146:147], v[214:215], v[222:223] op_sel_hi:[0,1,1] neg_lo:[1,0,0] neg_hi:[1,0,0]
	v_pk_fma_f32 v[138:139], v[138:139], v[216:217], v[220:221]
	v_pk_fma_f32 v[140:141], v[140:141], v[218:219], v[222:223]
	v_pk_mul_f32 v[144:145], v[138:139], v[230:231]
	v_pk_fma_f32 v[144:145], v[140:141], v[232:233], v[144:145]
	v_add_f32 v146, v144, v145
	ds_read_b128 v[186:189], v10 offset:26112
	ds_read_b128 v[190:193], v10 offset:26368
	ds_read_b128 v[194:197], v10 offset:26624
	ds_read_b128 v[198:201], v10 offset:26880
	ds_read_b128 v[202:205], v10 offset:27136
	ds_read_b32 v206, v11 offset:26112
	v_add_f32_dpp v146, v146, v146 quad_perm:[1,0,3,2] row_mask:0xf bank_mask:0xf bound_ctrl:1
	v_pk_mul_f32 v[224:225], v[138:139], v[224:225]
	v_pk_fma_f32 v[224:225], v[140:141], v[226:227], v[224:225]
	v_add_f32_dpp v146, v146, v146 quad_perm:[2,3,0,1] row_mask:0xf bank_mask:0xf bound_ctrl:1
	v_add_f32 v162, v224, v225
	v_pk_mul_f32 v[242:243], v[242:243], v[250:251] op_sel_hi:[1,0]
	v_add_f32_dpp v146, v146, v146 row_half_mirror row_mask:0xf bank_mask:0xf bound_ctrl:1
	v_pk_mul_f32 v[244:245], v[244:245], v[250:251] op_sel_hi:[1,0]
	s_waitcnt lgkmcnt(6)
	v_add_f32_dpp v146, v146, v146 row_mirror row_mask:0xf bank_mask:0xf bound_ctrl:1
	v_pk_fma_f32 v[242:243], v[146:147], v[234:235], v[242:243] op_sel_hi:[0,1,1] neg_lo:[1,0,0] neg_hi:[1,0,0]
	v_pk_fma_f32 v[244:245], v[146:147], v[236:237], v[244:245] op_sel_hi:[0,1,1] neg_lo:[1,0,0] neg_hi:[1,0,0]
	v_pk_fma_f32 v[138:139], v[138:139], v[238:239], v[242:243]
	v_pk_fma_f32 v[140:141], v[140:141], v[240:241], v[244:245]
	v_pk_mul_f32 v[144:145], v[138:139], v[164:165]
	v_pk_fma_f32 v[144:145], v[140:141], v[166:167], v[144:145]
	v_add_f32 v146, v144, v145
	ds_read_b128 v[208:211], v10 offset:27648
	ds_read_b128 v[212:215], v10 offset:27904
	ds_read_b128 v[216:219], v10 offset:28160
	ds_read_b128 v[220:223], v10 offset:28416
	ds_read_b128 v[224:227], v10 offset:28672
	ds_read_b32 v228, v11 offset:27648
	v_add_f32_dpp v146, v146, v146 quad_perm:[1,0,3,2] row_mask:0xf bank_mask:0xf bound_ctrl:1
	v_pk_mul_f32 v[246:247], v[138:139], v[246:247]
	v_pk_fma_f32 v[246:247], v[140:141], v[248:249], v[246:247]
	v_add_f32_dpp v146, v146, v146 quad_perm:[2,3,0,1] row_mask:0xf bank_mask:0xf bound_ctrl:1
	v_add_f32 v163, v246, v247
	v_pk_mul_f32 v[176:177], v[176:177], v[184:185] op_sel_hi:[1,0]
	v_add_f32_dpp v146, v146, v146 row_half_mirror row_mask:0xf bank_mask:0xf bound_ctrl:1
	v_pk_mul_f32 v[178:179], v[178:179], v[184:185] op_sel_hi:[1,0]
	s_waitcnt lgkmcnt(6)
	v_add_f32_dpp v146, v146, v146 row_mirror row_mask:0xf bank_mask:0xf bound_ctrl:1
	v_pk_fma_f32 v[176:177], v[146:147], v[168:169], v[176:177] op_sel_hi:[0,1,1] neg_lo:[1,0,0] neg_hi:[1,0,0]
	v_pk_fma_f32 v[178:179], v[146:147], v[170:171], v[178:179] op_sel_hi:[0,1,1] neg_lo:[1,0,0] neg_hi:[1,0,0]
	v_pk_fma_f32 v[138:139], v[138:139], v[172:173], v[176:177]
	v_pk_fma_f32 v[140:141], v[140:141], v[174:175], v[178:179]
	v_pk_mul_f32 v[144:145], v[138:139], v[186:187]
	v_pk_fma_f32 v[144:145], v[140:141], v[188:189], v[144:145]
	v_add_f32 v146, v144, v145
	v_add_f32_dpp v230, v148, v148 row_mirror row_mask:0xf bank_mask:0x3 bound_ctrl:1
	v_add_f32_dpp v230, v156, v156 row_mirror row_mask:0xf bank_mask:0xc bound_ctrl:1
	v_add_f32_dpp v231, v149, v149 row_mirror row_mask:0xf bank_mask:0x3 bound_ctrl:1
	v_add_f32_dpp v231, v157, v157 row_mirror row_mask:0xf bank_mask:0xc bound_ctrl:1
	v_add_f32_dpp v232, v150, v150 row_mirror row_mask:0xf bank_mask:0x3 bound_ctrl:1
	v_add_f32_dpp v232, v158, v158 row_mirror row_mask:0xf bank_mask:0xc bound_ctrl:1
	v_add_f32_dpp v233, v151, v151 row_mirror row_mask:0xf bank_mask:0x3 bound_ctrl:1
	v_add_f32_dpp v233, v159, v159 row_mirror row_mask:0xf bank_mask:0xc bound_ctrl:1
	v_add_f32_dpp v234, v152, v152 row_mirror row_mask:0xf bank_mask:0x3 bound_ctrl:1
	v_add_f32_dpp v234, v160, v160 row_mirror row_mask:0xf bank_mask:0xc bound_ctrl:1
	v_add_f32_dpp v235, v153, v153 row_mirror row_mask:0xf bank_mask:0x3 bound_ctrl:1
	v_add_f32_dpp v235, v161, v161 row_mirror row_mask:0xf bank_mask:0xc bound_ctrl:1
	v_add_f32_dpp v236, v154, v154 row_mirror row_mask:0xf bank_mask:0x3 bound_ctrl:1
	v_add_f32_dpp v236, v162, v162 row_mirror row_mask:0xf bank_mask:0xc bound_ctrl:1
	v_add_f32_dpp v237, v155, v155 row_mirror row_mask:0xf bank_mask:0x3 bound_ctrl:1
	v_add_f32_dpp v237, v163, v163 row_mirror row_mask:0xf bank_mask:0xc bound_ctrl:1
	v_add_f32_dpp v238, v230, v230 row_half_mirror row_mask:0xf bank_mask:0x5 bound_ctrl:1
	v_add_f32_dpp v238, v234, v234 row_half_mirror row_mask:0xf bank_mask:0xa bound_ctrl:1
	v_add_f32_dpp v239, v231, v231 row_half_mirror row_mask:0xf bank_mask:0x5 bound_ctrl:1
	v_add_f32_dpp v239, v235, v235 row_half_mirror row_mask:0xf bank_mask:0xa bound_ctrl:1
	v_add_f32_dpp v240, v232, v232 row_half_mirror row_mask:0xf bank_mask:0x5 bound_ctrl:1
	v_add_f32_dpp v240, v236, v236 row_half_mirror row_mask:0xf bank_mask:0xa bound_ctrl:1
	v_add_f32_dpp v241, v233, v233 row_half_mirror row_mask:0xf bank_mask:0x5 bound_ctrl:1
	v_add_f32_dpp v241, v237, v237 row_half_mirror row_mask:0xf bank_mask:0xa bound_ctrl:1
	s_mov_b32 vcc_lo, 0xcccccccc
	s_mov_b32 vcc_hi, 0xcccccccc
	v_cndmask_b32 v244, v240, v238, vcc
	v_cndmask_b32 v245, v241, v239, vcc
	v_cndmask_b32 v242, v238, v240, vcc
	v_cndmask_b32 v243, v239, v241, vcc
	v_add_f32_dpp v242, v244, v242 quad_perm:[2,3,0,1] row_mask:0xf bank_mask:0xf bound_ctrl:1
	v_add_f32_dpp v243, v245, v243 quad_perm:[2,3,0,1] row_mask:0xf bank_mask:0xf bound_ctrl:1
	s_mov_b32 vcc_lo, 0xaaaaaaaa
	s_mov_b32 vcc_hi, 0xaaaaaaaa
	v_cndmask_b32 v244, v243, v242, vcc
	v_cndmask_b32 v245, v242, v243, vcc
	s_nop 0
	v_add_f32_dpp v18, v244, v245 quad_perm:[1,0,3,2] row_mask:0xf bank_mask:0xf bound_ctrl:1
	ds_read_b128 v[230:233], v10 offset:29184
	ds_read_b128 v[234:237], v10 offset:29440
	ds_read_b128 v[238:241], v10 offset:29696
	ds_read_b128 v[242:245], v10 offset:29952
	ds_read_b128 v[246:249], v10 offset:30208
	ds_read_b32 v250, v11 offset:29184
	v_add_f32_dpp v146, v146, v146 quad_perm:[1,0,3,2] row_mask:0xf bank_mask:0xf bound_ctrl:1
	v_pk_mul_f32 v[180:181], v[138:139], v[180:181]
	v_pk_fma_f32 v[180:181], v[140:141], v[182:183], v[180:181]
	v_add_f32_dpp v146, v146, v146 quad_perm:[2,3,0,1] row_mask:0xf bank_mask:0xf bound_ctrl:1
	v_add_f32 v148, v180, v181
	v_pk_mul_f32 v[198:199], v[198:199], v[206:207] op_sel_hi:[1,0]
	v_add_f32_dpp v146, v146, v146 row_half_mirror row_mask:0xf bank_mask:0xf bound_ctrl:1
	v_pk_mul_f32 v[200:201], v[200:201], v[206:207] op_sel_hi:[1,0]
	s_waitcnt lgkmcnt(6)
	v_add_f32_dpp v146, v146, v146 row_mirror row_mask:0xf bank_mask:0xf bound_ctrl:1
	v_pk_fma_f32 v[198:199], v[146:147], v[190:191], v[198:199] op_sel_hi:[0,1,1] neg_lo:[1,0,0] neg_hi:[1,0,0]
	v_pk_fma_f32 v[200:201], v[146:147], v[192:193], v[200:201] op_sel_hi:[0,1,1] neg_lo:[1,0,0] neg_hi:[1,0,0]
	v_pk_fma_f32 v[138:139], v[138:139], v[194:195], v[198:199]
	v_pk_fma_f32 v[140:141], v[140:141], v[196:197], v[200:201]
	v_pk_mul_f32 v[144:145], v[138:139], v[208:209]
	v_pk_fma_f32 v[144:145], v[140:141], v[210:211], v[144:145]
	v_add_f32 v146, v144, v145
	ds_read_b128 v[164:167], v10 offset:30720
	ds_read_b128 v[168:171], v10 offset:30976
	ds_read_b128 v[172:175], v10 offset:31232
	ds_read_b128 v[176:179], v10 offset:31488
	ds_read_b128 v[180:183], v10 offset:31744
	ds_read_b32 v184, v11 offset:30720
	v_add_f32_dpp v146, v146, v146 quad_perm:[1,0,3,2] row_mask:0xf bank_mask:0xf bound_ctrl:1
	v_pk_mul_f32 v[202:203], v[138:139], v[202:203]
	v_pk_fma_f32 v[202:203], v[140:141], v[204:205], v[202:203]
	v_add_f32_dpp v146, v146, v146 quad_perm:[2,3,0,1] row_mask:0xf bank_mask:0xf bound_ctrl:1
	v_add_f32 v149, v202, v203
	v_pk_mul_f32 v[220:221], v[220:221], v[228:229] op_sel_hi:[1,0]
	v_add_f32_dpp v146, v146, v146 row_half_mirror row_mask:0xf bank_mask:0xf bound_ctrl:1
	v_pk_mul_f32 v[222:223], v[222:223], v[228:229] op_sel_hi:[1,0]
	s_waitcnt lgkmcnt(6)
	v_add_f32_dpp v146, v146, v146 row_mirror row_mask:0xf bank_mask:0xf bound_ctrl:1
	v_pk_fma_f32 v[220:221], v[146:147], v[212:213], v[220:221] op_sel_hi:[0,1,1] neg_lo:[1,0,0] neg_hi:[1,0,0]
	v_pk_fma_f32 v[222:223], v[146:147], v[214:215], v[222:223] op_sel_hi:[0,1,1] neg_lo:[1,0,0] neg_hi:[1,0,0]
	v_pk_fma_f32 v[138:139], v[138:139], v[216:217], v[220:221]
	v_pk_fma_f32 v[140:141], v[140:141], v[218:219], v[222:223]
	v_pk_mul_f32 v[144:145], v[138:139], v[230:231]
	v_pk_fma_f32 v[144:145], v[140:141], v[232:233], v[144:145]
	v_add_f32 v146, v144, v145
	ds_read_b128 v[186:189], v10 offset:32256
	ds_read_b128 v[190:193], v10 offset:32512
	ds_read_b128 v[194:197], v10 offset:32768
	ds_read_b128 v[198:201], v10 offset:33024
	ds_read_b128 v[202:205], v10 offset:33280
	ds_read_b32 v206, v11 offset:32256
	v_add_f32_dpp v146, v146, v146 quad_perm:[1,0,3,2] row_mask:0xf bank_mask:0xf bound_ctrl:1
	v_pk_mul_f32 v[224:225], v[138:139], v[224:225]
	v_pk_fma_f32 v[224:225], v[140:141], v[226:227], v[224:225]
	v_add_f32_dpp v146, v146, v146 quad_perm:[2,3,0,1] row_mask:0xf bank_mask:0xf bound_ctrl:1
	v_add_f32 v150, v224, v225
	v_pk_mul_f32 v[242:243], v[242:243], v[250:251] op_sel_hi:[1,0]
	v_add_f32_dpp v146, v146, v146 row_half_mirror row_mask:0xf bank_mask:0xf bound_ctrl:1
	v_pk_mul_f32 v[244:245], v[244:245], v[250:251] op_sel_hi:[1,0]
	s_waitcnt lgkmcnt(6)
	v_add_f32_dpp v146, v146, v146 row_mirror row_mask:0xf bank_mask:0xf bound_ctrl:1
	v_pk_fma_f32 v[242:243], v[146:147], v[234:235], v[242:243] op_sel_hi:[0,1,1] neg_lo:[1,0,0] neg_hi:[1,0,0]
	v_pk_fma_f32 v[244:245], v[146:147], v[236:237], v[244:245] op_sel_hi:[0,1,1] neg_lo:[1,0,0] neg_hi:[1,0,0]
	v_pk_fma_f32 v[138:139], v[138:139], v[238:239], v[242:243]
	v_pk_fma_f32 v[140:141], v[140:141], v[240:241], v[244:245]
	v_pk_mul_f32 v[144:145], v[138:139], v[164:165]
	v_pk_fma_f32 v[144:145], v[140:141], v[166:167], v[144:145]
	v_add_f32 v146, v144, v145
	ds_read_b128 v[208:211], v10 offset:33792
	ds_read_b128 v[212:215], v10 offset:34048
	ds_read_b128 v[216:219], v10 offset:34304
	ds_read_b128 v[220:223], v10 offset:34560
	ds_read_b128 v[224:227], v10 offset:34816
	ds_read_b32 v228, v11 offset:33792
	v_add_f32_dpp v146, v146, v146 quad_perm:[1,0,3,2] row_mask:0xf bank_mask:0xf bound_ctrl:1
	v_pk_mul_f32 v[246:247], v[138:139], v[246:247]
	v_pk_fma_f32 v[246:247], v[140:141], v[248:249], v[246:247]
	v_add_f32_dpp v146, v146, v146 quad_perm:[2,3,0,1] row_mask:0xf bank_mask:0xf bound_ctrl:1
	v_add_f32 v151, v246, v247
	v_pk_mul_f32 v[176:177], v[176:177], v[184:185] op_sel_hi:[1,0]
	v_add_f32_dpp v146, v146, v146 row_half_mirror row_mask:0xf bank_mask:0xf bound_ctrl:1
	v_pk_mul_f32 v[178:179], v[178:179], v[184:185] op_sel_hi:[1,0]
	s_waitcnt lgkmcnt(6)
	v_add_f32_dpp v146, v146, v146 row_mirror row_mask:0xf bank_mask:0xf bound_ctrl:1
	v_pk_fma_f32 v[176:177], v[146:147], v[168:169], v[176:177] op_sel_hi:[0,1,1] neg_lo:[1,0,0] neg_hi:[1,0,0]
	v_pk_fma_f32 v[178:179], v[146:147], v[170:171], v[178:179] op_sel_hi:[0,1,1] neg_lo:[1,0,0] neg_hi:[1,0,0]
	v_pk_fma_f32 v[138:139], v[138:139], v[172:173], v[176:177]
	v_pk_fma_f32 v[140:141], v[140:141], v[174:175], v[178:179]
	v_pk_mul_f32 v[144:145], v[138:139], v[186:187]
	v_pk_fma_f32 v[144:145], v[140:141], v[188:189], v[144:145]
	v_add_f32 v146, v144, v145
	ds_read_b128 v[230:233], v10 offset:35328
	ds_read_b128 v[234:237], v10 offset:35584
	ds_read_b128 v[238:241], v10 offset:35840
	ds_read_b128 v[242:245], v10 offset:36096
	ds_read_b128 v[246:249], v10 offset:36352
	ds_read_b32 v250, v11 offset:35328
	v_add_f32_dpp v146, v146, v146 quad_perm:[1,0,3,2] row_mask:0xf bank_mask:0xf bound_ctrl:1
	v_pk_mul_f32 v[180:181], v[138:139], v[180:181]
	v_pk_fma_f32 v[180:181], v[140:141], v[182:183], v[180:181]
	v_add_f32_dpp v146, v146, v146 quad_perm:[2,3,0,1] row_mask:0xf bank_mask:0xf bound_ctrl:1
	v_add_f32 v152, v180, v181
	v_pk_mul_f32 v[198:199], v[198:199], v[206:207] op_sel_hi:[1,0]
	v_add_f32_dpp v146, v146, v146 row_half_mirror row_mask:0xf bank_mask:0xf bound_ctrl:1
	v_pk_mul_f32 v[200:201], v[200:201], v[206:207] op_sel_hi:[1,0]
	s_waitcnt lgkmcnt(6)
	v_add_f32_dpp v146, v146, v146 row_mirror row_mask:0xf bank_mask:0xf bound_ctrl:1
	v_pk_fma_f32 v[198:199], v[146:147], v[190:191], v[198:199] op_sel_hi:[0,1,1] neg_lo:[1,0,0] neg_hi:[1,0,0]
	v_pk_fma_f32 v[200:201], v[146:147], v[192:193], v[200:201] op_sel_hi:[0,1,1] neg_lo:[1,0,0] neg_hi:[1,0,0]
	v_pk_fma_f32 v[138:139], v[138:139], v[194:195], v[198:199]
	v_pk_fma_f32 v[140:141], v[140:141], v[196:197], v[200:201]
	v_pk_mul_f32 v[144:145], v[138:139], v[208:209]
	v_pk_fma_f32 v[144:145], v[140:141], v[210:211], v[144:145]
	v_add_f32 v146, v144, v145
	ds_read_b128 v[164:167], v10 offset:36864
	ds_read_b128 v[168:171], v10 offset:37120
	ds_read_b128 v[172:175], v10 offset:37376
	ds_read_b128 v[176:179], v10 offset:37632
	ds_read_b128 v[180:183], v10 offset:37888
	ds_read_b32 v184, v11 offset:36864
	v_add_f32_dpp v146, v146, v146 quad_perm:[1,0,3,2] row_mask:0xf bank_mask:0xf bound_ctrl:1
	v_pk_mul_f32 v[202:203], v[138:139], v[202:203]
	v_pk_fma_f32 v[202:203], v[140:141], v[204:205], v[202:203]
	v_add_f32_dpp v146, v146, v146 quad_perm:[2,3,0,1] row_mask:0xf bank_mask:0xf bound_ctrl:1
	v_add_f32 v153, v202, v203
	v_pk_mul_f32 v[220:221], v[220:221], v[228:229] op_sel_hi:[1,0]
	v_add_f32_dpp v146, v146, v146 row_half_mirror row_mask:0xf bank_mask:0xf bound_ctrl:1
	v_pk_mul_f32 v[222:223], v[222:223], v[228:229] op_sel_hi:[1,0]
	s_waitcnt lgkmcnt(6)
	v_add_f32_dpp v146, v146, v146 row_mirror row_mask:0xf bank_mask:0xf bound_ctrl:1
	v_pk_fma_f32 v[220:221], v[146:147], v[212:213], v[220:221] op_sel_hi:[0,1,1] neg_lo:[1,0,0] neg_hi:[1,0,0]
	v_pk_fma_f32 v[222:223], v[146:147], v[214:215], v[222:223] op_sel_hi:[0,1,1] neg_lo:[1,0,0] neg_hi:[1,0,0]
	v_pk_fma_f32 v[138:139], v[138:139], v[216:217], v[220:221]
	v_pk_fma_f32 v[140:141], v[140:141], v[218:219], v[222:223]
	v_pk_mul_f32 v[144:145], v[138:139], v[230:231]
	v_pk_fma_f32 v[144:145], v[140:141], v[232:233], v[144:145]
	v_add_f32 v146, v144, v145
	ds_read_b128 v[186:189], v10 offset:38400
	ds_read_b128 v[190:193], v10 offset:38656
	ds_read_b128 v[194:197], v10 offset:38912
	ds_read_b128 v[198:201], v10 offset:39168
	ds_read_b128 v[202:205], v10 offset:39424
	ds_read_b32 v206, v11 offset:38400
	v_add_f32_dpp v146, v146, v146 quad_perm:[1,0,3,2] row_mask:0xf bank_mask:0xf bound_ctrl:1
	v_pk_mul_f32 v[224:225], v[138:139], v[224:225]
	v_pk_fma_f32 v[224:225], v[140:141], v[226:227], v[224:225]
	v_add_f32_dpp v146, v146, v146 quad_perm:[2,3,0,1] row_mask:0xf bank_mask:0xf bound_ctrl:1
	v_add_f32 v154, v224, v225
	v_pk_mul_f32 v[242:243], v[242:243], v[250:251] op_sel_hi:[1,0]
	v_add_f32_dpp v146, v146, v146 row_half_mirror row_mask:0xf bank_mask:0xf bound_ctrl:1
	v_pk_mul_f32 v[244:245], v[244:245], v[250:251] op_sel_hi:[1,0]
	s_waitcnt lgkmcnt(6)
	v_add_f32_dpp v146, v146, v146 row_mirror row_mask:0xf bank_mask:0xf bound_ctrl:1
	v_pk_fma_f32 v[242:243], v[146:147], v[234:235], v[242:243] op_sel_hi:[0,1,1] neg_lo:[1,0,0] neg_hi:[1,0,0]
	v_pk_fma_f32 v[244:245], v[146:147], v[236:237], v[244:245] op_sel_hi:[0,1,1] neg_lo:[1,0,0] neg_hi:[1,0,0]
	v_pk_fma_f32 v[138:139], v[138:139], v[238:239], v[242:243]
	v_pk_fma_f32 v[140:141], v[140:141], v[240:241], v[244:245]
	v_pk_mul_f32 v[144:145], v[138:139], v[164:165]
	v_pk_fma_f32 v[144:145], v[140:141], v[166:167], v[144:145]
	v_add_f32 v146, v144, v145
	ds_read_b128 v[208:211], v10 offset:39936
	ds_read_b128 v[212:215], v10 offset:40192
	ds_read_b128 v[216:219], v10 offset:40448
	ds_read_b128 v[220:223], v10 offset:40704
	ds_read_b128 v[224:227], v10 offset:40960
	ds_read_b32 v228, v11 offset:39936
	v_add_f32_dpp v146, v146, v146 quad_perm:[1,0,3,2] row_mask:0xf bank_mask:0xf bound_ctrl:1
	v_pk_mul_f32 v[246:247], v[138:139], v[246:247]
	v_pk_fma_f32 v[246:247], v[140:141], v[248:249], v[246:247]
	v_add_f32_dpp v146, v146, v146 quad_perm:[2,3,0,1] row_mask:0xf bank_mask:0xf bound_ctrl:1
	v_add_f32 v155, v246, v247
	v_pk_mul_f32 v[176:177], v[176:177], v[184:185] op_sel_hi:[1,0]
	v_add_f32_dpp v146, v146, v146 row_half_mirror row_mask:0xf bank_mask:0xf bound_ctrl:1
	v_pk_mul_f32 v[178:179], v[178:179], v[184:185] op_sel_hi:[1,0]
	s_waitcnt lgkmcnt(6)
	v_add_f32_dpp v146, v146, v146 row_mirror row_mask:0xf bank_mask:0xf bound_ctrl:1
	v_pk_fma_f32 v[176:177], v[146:147], v[168:169], v[176:177] op_sel_hi:[0,1,1] neg_lo:[1,0,0] neg_hi:[1,0,0]
	v_pk_fma_f32 v[178:179], v[146:147], v[170:171], v[178:179] op_sel_hi:[0,1,1] neg_lo:[1,0,0] neg_hi:[1,0,0]
	v_pk_fma_f32 v[138:139], v[138:139], v[172:173], v[176:177]
	v_pk_fma_f32 v[140:141], v[140:141], v[174:175], v[178:179]
	v_pk_mul_f32 v[144:145], v[138:139], v[186:187]
	v_pk_fma_f32 v[144:145], v[140:141], v[188:189], v[144:145]
	v_add_f32 v146, v144, v145
	ds_read_b128 v[230:233], v10 offset:41472
	ds_read_b128 v[234:237], v10 offset:41728
	ds_read_b128 v[238:241], v10 offset:41984
	ds_read_b128 v[242:245], v10 offset:42240
	ds_read_b128 v[246:249], v10 offset:42496
	ds_read_b32 v250, v11 offset:41472
	v_add_f32_dpp v146, v146, v146 quad_perm:[1,0,3,2] row_mask:0xf bank_mask:0xf bound_ctrl:1
	v_pk_mul_f32 v[180:181], v[138:139], v[180:181]
	v_pk_fma_f32 v[180:181], v[140:141], v[182:183], v[180:181]
	v_add_f32_dpp v146, v146, v146 quad_perm:[2,3,0,1] row_mask:0xf bank_mask:0xf bound_ctrl:1
	v_add_f32 v156, v180, v181
	v_pk_mul_f32 v[198:199], v[198:199], v[206:207] op_sel_hi:[1,0]
	v_add_f32_dpp v146, v146, v146 row_half_mirror row_mask:0xf bank_mask:0xf bound_ctrl:1
	v_pk_mul_f32 v[200:201], v[200:201], v[206:207] op_sel_hi:[1,0]
	s_waitcnt lgkmcnt(6)
	v_add_f32_dpp v146, v146, v146 row_mirror row_mask:0xf bank_mask:0xf bound_ctrl:1
	v_pk_fma_f32 v[198:199], v[146:147], v[190:191], v[198:199] op_sel_hi:[0,1,1] neg_lo:[1,0,0] neg_hi:[1,0,0]
	v_pk_fma_f32 v[200:201], v[146:147], v[192:193], v[200:201] op_sel_hi:[0,1,1] neg_lo:[1,0,0] neg_hi:[1,0,0]
	v_pk_fma_f32 v[138:139], v[138:139], v[194:195], v[198:199]
	v_pk_fma_f32 v[140:141], v[140:141], v[196:197], v[200:201]
	v_pk_mul_f32 v[144:145], v[138:139], v[208:209]
	v_pk_fma_f32 v[144:145], v[140:141], v[210:211], v[144:145]
	v_add_f32 v146, v144, v145
	ds_read_b128 v[164:167], v10 offset:43008
	ds_read_b128 v[168:171], v10 offset:43264
	ds_read_b128 v[172:175], v10 offset:43520
	ds_read_b128 v[176:179], v10 offset:43776
	ds_read_b128 v[180:183], v10 offset:44032
	ds_read_b32 v184, v11 offset:43008
	v_add_f32_dpp v146, v146, v146 quad_perm:[1,0,3,2] row_mask:0xf bank_mask:0xf bound_ctrl:1
	v_pk_mul_f32 v[202:203], v[138:139], v[202:203]
	v_pk_fma_f32 v[202:203], v[140:141], v[204:205], v[202:203]
	v_add_f32_dpp v146, v146, v146 quad_perm:[2,3,0,1] row_mask:0xf bank_mask:0xf bound_ctrl:1
	v_add_f32 v157, v202, v203
	v_pk_mul_f32 v[220:221], v[220:221], v[228:229] op_sel_hi:[1,0]
	v_add_f32_dpp v146, v146, v146 row_half_mirror row_mask:0xf bank_mask:0xf bound_ctrl:1
	v_pk_mul_f32 v[222:223], v[222:223], v[228:229] op_sel_hi:[1,0]
	s_waitcnt lgkmcnt(6)
	v_add_f32_dpp v146, v146, v146 row_mirror row_mask:0xf bank_mask:0xf bound_ctrl:1
	v_pk_fma_f32 v[220:221], v[146:147], v[212:213], v[220:221] op_sel_hi:[0,1,1] neg_lo:[1,0,0] neg_hi:[1,0,0]
	v_pk_fma_f32 v[222:223], v[146:147], v[214:215], v[222:223] op_sel_hi:[0,1,1] neg_lo:[1,0,0] neg_hi:[1,0,0]
	v_pk_fma_f32 v[138:139], v[138:139], v[216:217], v[220:221]
	v_pk_fma_f32 v[140:141], v[140:141], v[218:219], v[222:223]
	v_pk_mul_f32 v[144:145], v[138:139], v[230:231]
	v_pk_fma_f32 v[144:145], v[140:141], v[232:233], v[144:145]
	v_add_f32 v146, v144, v145
	ds_read_b128 v[186:189], v10 offset:44544
	ds_read_b128 v[190:193], v10 offset:44800
	ds_read_b128 v[194:197], v10 offset:45056
	ds_read_b128 v[198:201], v10 offset:45312
	ds_read_b128 v[202:205], v10 offset:45568
	ds_read_b32 v206, v11 offset:44544
	v_add_f32_dpp v146, v146, v146 quad_perm:[1,0,3,2] row_mask:0xf bank_mask:0xf bound_ctrl:1
	v_pk_mul_f32 v[224:225], v[138:139], v[224:225]
	v_pk_fma_f32 v[224:225], v[140:141], v[226:227], v[224:225]
	v_add_f32_dpp v146, v146, v146 quad_perm:[2,3,0,1] row_mask:0xf bank_mask:0xf bound_ctrl:1
	v_add_f32 v158, v224, v225
	v_pk_mul_f32 v[242:243], v[242:243], v[250:251] op_sel_hi:[1,0]
	v_add_f32_dpp v146, v146, v146 row_half_mirror row_mask:0xf bank_mask:0xf bound_ctrl:1
	v_pk_mul_f32 v[244:245], v[244:245], v[250:251] op_sel_hi:[1,0]
	s_waitcnt lgkmcnt(6)
	v_add_f32_dpp v146, v146, v146 row_mirror row_mask:0xf bank_mask:0xf bound_ctrl:1
	v_pk_fma_f32 v[242:243], v[146:147], v[234:235], v[242:243] op_sel_hi:[0,1,1] neg_lo:[1,0,0] neg_hi:[1,0,0]
	v_pk_fma_f32 v[244:245], v[146:147], v[236:237], v[244:245] op_sel_hi:[0,1,1] neg_lo:[1,0,0] neg_hi:[1,0,0]
	v_pk_fma_f32 v[138:139], v[138:139], v[238:239], v[242:243]
	v_pk_fma_f32 v[140:141], v[140:141], v[240:241], v[244:245]
	v_pk_mul_f32 v[144:145], v[138:139], v[164:165]
	v_pk_fma_f32 v[144:145], v[140:141], v[166:167], v[144:145]
	v_add_f32 v146, v144, v145
	ds_read_b128 v[208:211], v10 offset:46080
	ds_read_b128 v[212:215], v10 offset:46336
	ds_read_b128 v[216:219], v10 offset:46592
	ds_read_b128 v[220:223], v10 offset:46848
	ds_read_b128 v[224:227], v10 offset:47104
	ds_read_b32 v228, v11 offset:46080
	v_add_f32_dpp v146, v146, v146 quad_perm:[1,0,3,2] row_mask:0xf bank_mask:0xf bound_ctrl:1
	v_pk_mul_f32 v[246:247], v[138:139], v[246:247]
	v_pk_fma_f32 v[246:247], v[140:141], v[248:249], v[246:247]
	v_add_f32_dpp v146, v146, v146 quad_perm:[2,3,0,1] row_mask:0xf bank_mask:0xf bound_ctrl:1
	v_add_f32 v159, v246, v247
	v_pk_mul_f32 v[176:177], v[176:177], v[184:185] op_sel_hi:[1,0]
	v_add_f32_dpp v146, v146, v146 row_half_mirror row_mask:0xf bank_mask:0xf bound_ctrl:1
	v_pk_mul_f32 v[178:179], v[178:179], v[184:185] op_sel_hi:[1,0]
	s_waitcnt lgkmcnt(6)
	v_add_f32_dpp v146, v146, v146 row_mirror row_mask:0xf bank_mask:0xf bound_ctrl:1
	v_pk_fma_f32 v[176:177], v[146:147], v[168:169], v[176:177] op_sel_hi:[0,1,1] neg_lo:[1,0,0] neg_hi:[1,0,0]
	v_pk_fma_f32 v[178:179], v[146:147], v[170:171], v[178:179] op_sel_hi:[0,1,1] neg_lo:[1,0,0] neg_hi:[1,0,0]
	v_pk_fma_f32 v[138:139], v[138:139], v[172:173], v[176:177]
	v_pk_fma_f32 v[140:141], v[140:141], v[174:175], v[178:179]
	v_pk_mul_f32 v[144:145], v[138:139], v[186:187]
	v_pk_fma_f32 v[144:145], v[140:141], v[188:189], v[144:145]
	v_add_f32 v146, v144, v145
	ds_read_b128 v[230:233], v10 offset:47616
	ds_read_b128 v[234:237], v10 offset:47872
	ds_read_b128 v[238:241], v10 offset:48128
	ds_read_b128 v[242:245], v10 offset:48384
	ds_read_b128 v[246:249], v10 offset:48640
	ds_read_b32 v250, v11 offset:47616
	v_add_f32_dpp v146, v146, v146 quad_perm:[1,0,3,2] row_mask:0xf bank_mask:0xf bound_ctrl:1
	v_pk_mul_f32 v[180:181], v[138:139], v[180:181]
	v_pk_fma_f32 v[180:181], v[140:141], v[182:183], v[180:181]
	v_add_f32_dpp v146, v146, v146 quad_perm:[2,3,0,1] row_mask:0xf bank_mask:0xf bound_ctrl:1
	v_add_f32 v160, v180, v181
	v_pk_mul_f32 v[198:199], v[198:199], v[206:207] op_sel_hi:[1,0]
	v_add_f32_dpp v146, v146, v146 row_half_mirror row_mask:0xf bank_mask:0xf bound_ctrl:1
	v_pk_mul_f32 v[200:201], v[200:201], v[206:207] op_sel_hi:[1,0]
	s_waitcnt lgkmcnt(6)
	v_add_f32_dpp v146, v146, v146 row_mirror row_mask:0xf bank_mask:0xf bound_ctrl:1
	v_pk_fma_f32 v[198:199], v[146:147], v[190:191], v[198:199] op_sel_hi:[0,1,1] neg_lo:[1,0,0] neg_hi:[1,0,0]
	v_pk_fma_f32 v[200:201], v[146:147], v[192:193], v[200:201] op_sel_hi:[0,1,1] neg_lo:[1,0,0] neg_hi:[1,0,0]
	v_pk_fma_f32 v[138:139], v[138:139], v[194:195], v[198:199]
	v_pk_fma_f32 v[140:141], v[140:141], v[196:197], v[200:201]
	v_pk_mul_f32 v[144:145], v[138:139], v[208:209]
	v_pk_fma_f32 v[144:145], v[140:141], v[210:211], v[144:145]
	v_add_f32 v146, v144, v145
	s_nop 1
	v_add_f32_dpp v146, v146, v146 quad_perm:[1,0,3,2] row_mask:0xf bank_mask:0xf bound_ctrl:1
	v_pk_mul_f32 v[202:203], v[138:139], v[202:203]
	v_pk_fma_f32 v[202:203], v[140:141], v[204:205], v[202:203]
	v_add_f32_dpp v146, v146, v146 quad_perm:[2,3,0,1] row_mask:0xf bank_mask:0xf bound_ctrl:1
	v_add_f32 v161, v202, v203
	v_pk_mul_f32 v[220:221], v[220:221], v[228:229] op_sel_hi:[1,0]
	v_add_f32_dpp v146, v146, v146 row_half_mirror row_mask:0xf bank_mask:0xf bound_ctrl:1
	v_pk_mul_f32 v[222:223], v[222:223], v[228:229] op_sel_hi:[1,0]
	s_waitcnt lgkmcnt(0)
	v_add_f32_dpp v146, v146, v146 row_mirror row_mask:0xf bank_mask:0xf bound_ctrl:1
	v_pk_fma_f32 v[220:221], v[146:147], v[212:213], v[220:221] op_sel_hi:[0,1,1] neg_lo:[1,0,0] neg_hi:[1,0,0]
	v_pk_fma_f32 v[222:223], v[146:147], v[214:215], v[222:223] op_sel_hi:[0,1,1] neg_lo:[1,0,0] neg_hi:[1,0,0]
	v_pk_fma_f32 v[138:139], v[138:139], v[216:217], v[220:221]
	v_pk_fma_f32 v[140:141], v[140:141], v[218:219], v[222:223]
	v_pk_mul_f32 v[144:145], v[138:139], v[230:231]
	v_pk_fma_f32 v[144:145], v[140:141], v[232:233], v[144:145]
	v_add_f32 v146, v144, v145
	s_nop 1
	v_add_f32_dpp v146, v146, v146 quad_perm:[1,0,3,2] row_mask:0xf bank_mask:0xf bound_ctrl:1
	v_pk_mul_f32 v[224:225], v[138:139], v[224:225]
	v_pk_fma_f32 v[224:225], v[140:141], v[226:227], v[224:225]
	v_add_f32_dpp v146, v146, v146 quad_perm:[2,3,0,1] row_mask:0xf bank_mask:0xf bound_ctrl:1
	v_add_f32 v162, v224, v225
	v_pk_mul_f32 v[242:243], v[242:243], v[250:251] op_sel_hi:[1,0]
	v_add_f32_dpp v146, v146, v146 row_half_mirror row_mask:0xf bank_mask:0xf bound_ctrl:1
	v_pk_mul_f32 v[244:245], v[244:245], v[250:251] op_sel_hi:[1,0]
	s_nop 0
	v_add_f32_dpp v146, v146, v146 row_mirror row_mask:0xf bank_mask:0xf bound_ctrl:1
	v_pk_fma_f32 v[242:243], v[146:147], v[234:235], v[242:243] op_sel_hi:[0,1,1] neg_lo:[1,0,0] neg_hi:[1,0,0]
	v_pk_fma_f32 v[244:245], v[146:147], v[236:237], v[244:245] op_sel_hi:[0,1,1] neg_lo:[1,0,0] neg_hi:[1,0,0]
	v_pk_fma_f32 v[138:139], v[138:139], v[238:239], v[242:243]
	v_pk_fma_f32 v[140:141], v[140:141], v[240:241], v[244:245]
	v_pk_mul_f32 v[246:247], v[138:139], v[246:247]
	v_pk_fma_f32 v[246:247], v[140:141], v[248:249], v[246:247]
	v_add_f32 v163, v246, v247
	s_nop 0
	v_add_f32_dpp v230, v148, v148 row_mirror row_mask:0xf bank_mask:0x3 bound_ctrl:1
	v_add_f32_dpp v230, v156, v156 row_mirror row_mask:0xf bank_mask:0xc bound_ctrl:1
	v_add_f32_dpp v231, v149, v149 row_mirror row_mask:0xf bank_mask:0x3 bound_ctrl:1
	v_add_f32_dpp v231, v157, v157 row_mirror row_mask:0xf bank_mask:0xc bound_ctrl:1
	v_add_f32_dpp v232, v150, v150 row_mirror row_mask:0xf bank_mask:0x3 bound_ctrl:1
	v_add_f32_dpp v232, v158, v158 row_mirror row_mask:0xf bank_mask:0xc bound_ctrl:1
	v_add_f32_dpp v233, v151, v151 row_mirror row_mask:0xf bank_mask:0x3 bound_ctrl:1
	v_add_f32_dpp v233, v159, v159 row_mirror row_mask:0xf bank_mask:0xc bound_ctrl:1
	v_add_f32_dpp v234, v152, v152 row_mirror row_mask:0xf bank_mask:0x3 bound_ctrl:1
	v_add_f32_dpp v234, v160, v160 row_mirror row_mask:0xf bank_mask:0xc bound_ctrl:1
	v_add_f32_dpp v235, v153, v153 row_mirror row_mask:0xf bank_mask:0x3 bound_ctrl:1
	v_add_f32_dpp v235, v161, v161 row_mirror row_mask:0xf bank_mask:0xc bound_ctrl:1
	v_add_f32_dpp v236, v154, v154 row_mirror row_mask:0xf bank_mask:0x3 bound_ctrl:1
	v_add_f32_dpp v236, v162, v162 row_mirror row_mask:0xf bank_mask:0xc bound_ctrl:1
	v_add_f32_dpp v237, v155, v155 row_mirror row_mask:0xf bank_mask:0x3 bound_ctrl:1
	v_add_f32_dpp v237, v163, v163 row_mirror row_mask:0xf bank_mask:0xc bound_ctrl:1
	v_add_f32_dpp v238, v230, v230 row_half_mirror row_mask:0xf bank_mask:0x5 bound_ctrl:1
	v_add_f32_dpp v238, v234, v234 row_half_mirror row_mask:0xf bank_mask:0xa bound_ctrl:1
	v_add_f32_dpp v239, v231, v231 row_half_mirror row_mask:0xf bank_mask:0x5 bound_ctrl:1
	v_add_f32_dpp v239, v235, v235 row_half_mirror row_mask:0xf bank_mask:0xa bound_ctrl:1
	v_add_f32_dpp v240, v232, v232 row_half_mirror row_mask:0xf bank_mask:0x5 bound_ctrl:1
	v_add_f32_dpp v240, v236, v236 row_half_mirror row_mask:0xf bank_mask:0xa bound_ctrl:1
	v_add_f32_dpp v241, v233, v233 row_half_mirror row_mask:0xf bank_mask:0x5 bound_ctrl:1
	v_add_f32_dpp v241, v237, v237 row_half_mirror row_mask:0xf bank_mask:0xa bound_ctrl:1
	s_mov_b32 vcc_lo, 0xcccccccc
	s_mov_b32 vcc_hi, 0xcccccccc
	v_cndmask_b32 v244, v240, v238, vcc
	v_cndmask_b32 v245, v241, v239, vcc
	v_cndmask_b32 v242, v238, v240, vcc
	v_cndmask_b32 v243, v239, v241, vcc
	v_add_f32_dpp v242, v244, v242 quad_perm:[2,3,0,1] row_mask:0xf bank_mask:0xf bound_ctrl:1
	v_add_f32_dpp v243, v245, v243 quad_perm:[2,3,0,1] row_mask:0xf bank_mask:0xf bound_ctrl:1
	s_mov_b32 vcc_lo, 0xaaaaaaaa
	s_mov_b32 vcc_hi, 0xaaaaaaaa
	v_cndmask_b32 v244, v243, v242, vcc
	v_cndmask_b32 v245, v242, v243, vcc
	s_nop 0
	v_add_f32_dpp v19, v244, v245 quad_perm:[1,0,3,2] row_mask:0xf bank_mask:0xf bound_ctrl:1

; #define SCAN_BAR() asm volatile("s_barrier" ::: "memory")
; __device__ __forceinline__ void scan_unit(const Ctx& C0, const float* scn, int T, int quarter, const float* S0, float* Sout, unsigned char* obase, int mode) {
;     ...
;             asm volatile(SCAN_CHUNK_ASM : "+v"(S0x), "+v"(S1x), "+v"(S2x), "+v"(S3x), "=&v"(osel0), "=&v"(osel1) : "v"(aq), "v"(av), "v"(q) : SCAN_CHUNK_CLOBBERS, "memory");
;             if (mode == 0) { *(float*)(obase + (size_t)(k * 32 + q) * UPITCH_B + rl * 4) = osel0; *(float*)(obase + (size_t)(k * 32 + 16 + q) * UPITCH_B + rl * 4) = osel1; }
;             SCAN_BAR();
;         }
;         if (mode == 0) *(f32x4*)(Sout + irow * 64 + 4 * q) = (f32x4){S0x, S1x, S2x, S3x};
	s_barrier
	ds_read_b128 v[164:167], v5 offset:0
	ds_read_b128 v[168:171], v5 offset:256
	ds_read_b128 v[172:175], v5 offset:512
	ds_read_b128 v[176:179], v5 offset:768
	ds_read_b128 v[180:183], v5 offset:1024
	ds_read_b32 v184, v9 offset:0
	ds_read_b128 v[186:189], v5 offset:1536
	ds_read_b128 v[190:193], v5 offset:1792
	ds_read_b128 v[194:197], v5 offset:2048
	ds_read_b128 v[198:201], v5 offset:2304
	ds_read_b128 v[202:205], v5 offset:2560
	ds_read_b32 v206, v9 offset:1536
	s_addc_u32 s1, s1, 0
	v_add_co_u32_e32 v16, vcc, s8, v14
	s_cmp_lg_u32 s0, 0x5600000
	s_nop 0
	v_addc_co_u32_e32 v17, vcc, 0, v15, vcc
	v_add_co_u32_e32 v14, vcc, 0xfcaa000, v14
	global_store_dword v[16:17], v18, off offset:768
	s_nop 0
	v_addc_co_u32_e32 v15, vcc, 0, v15, vcc
	global_store_dword v[14:15], v19, off offset:768
	s_cbranch_scc1 .LBB0_685
	v_mov_b32_e32 v2, v138
	v_mov_b32_e32 v13, v139
	v_mov_b32_e32 v12, v140
	v_mov_b32_e32 v8, v141
	v_readlane_b32 s0, v255, 46
	s_add_i32 s0, s3, s0
	s_ashr_i32 s1, s0, 31
	s_lshl_b64 s[0:1], s[0:1], 17
	v_readlane_b32 s3, v253, 26
	s_add_u32 s0, s3, s0
	v_readlane_b32 s3, v253, 27
	s_addc_u32 s1, s3, s1
	s_lshl_b32 s2, s2, 14
	s_add_u32 s0, s0, s2
	s_addc_u32 s1, s1, 0
	v_lshlrev_b32_e32 v0, 8, v0
	v_lshl_add_u64 v[6:7], s[0:1], 0, v[0:1]
	v_mov_b32_e32 v5, v1
	v_lshl_add_u64 v[6:7], v[6:7], 0, v[4:5]
	v_mov_b32_e32 v3, v13
	v_mov_b32_e32 v4, v12
	v_mov_b32_e32 v5, v8
	global_store_dwordx4 v[6:7], v[2:5], off
